# v37: + S5B epilogue pipelined, cmp_item K loop and w2 loop loads hoisted with counted waits, gMLP spatial-gate loads hoisted in the E2 gridDim==256 instance (the earlier rewrite had hit the generic fa
# speedup vs baseline: 1.0199x; 1.0199x over previous
.LBB0_1212:
	v_add_u32_e32 v145, s33, v153
	v_add_u32_e32 v142, s20, v145
	v_ashrrev_i32_e32 v143, 31, v142
	v_or_b32_e32 v158, s11, v154
	v_lshlrev_b64 v[142:143], 10, v[142:143]
	v_lshl_add_u64 v[142:143], s[4:5], 0, v[142:143]
	v_lshlrev_b32_e32 v0, 2, v158
	v_lshl_add_u64 v[150:151], v[142:143], 0, v[0:1]
	s_lshl_b32 s0, s10, 4
	s_ashr_i32 s1, s0, 31
	v_lshrrev_b32_e32 v144, 4, v158
	v_lshlrev_b32_e32 v159, 4, v145
	v_and_b32_e32 v142, 8, v152
	s_lshl_b64 s[0:1], s[0:1], 1
	v_or_b32_e32 v152, v159, v144
	s_add_u32 s0, s92, s0
	v_ashrrev_i32_e32 v153, 31, v152
	s_addc_u32 s1, s93, s1
	v_lshlrev_b64 v[152:153], 10, v[152:153]
	v_mov_b32_e32 v143, v1
	v_lshlrev_b32_e32 v142, 1, v142
	v_lshl_add_u64 v[152:153], s[0:1], 0, v[152:153]
	v_lshl_add_u64 v[152:153], v[152:153], 0, v[142:143]
	s_mov_b32 s28, s96
	v_mov_b32_e32 v244, v150
	v_mov_b32_e32 v245, v151
	v_add_co_u32_e32 v246, vcc, 0x2000, v152
	s_nop 1
	v_addc_co_u32_e32 v247, vcc, 0, v153, vcc
	global_load_dwordx4 v[196:199], v[244:245], off
	global_load_dwordx4 v[200:203], v[244:245], off offset:16
	global_load_dwordx4 v[204:207], v[244:245], off offset:512
	global_load_dwordx4 v[208:211], v[244:245], off offset:528
	v_add_co_u32_e32 v244, vcc, 0x4000, v244
	s_nop 1
	v_addc_co_u32_e32 v245, vcc, 0, v245, vcc
	global_load_dwordx4 v[212:215], v[244:245], off
	global_load_dwordx4 v[216:219], v[244:245], off offset:16
	global_load_dwordx4 v[220:223], v[244:245], off offset:512
	global_load_dwordx4 v[224:227], v[244:245], off offset:528
	v_add_co_u32_e32 v244, vcc, 0x4000, v244
	s_nop 1
	v_addc_co_u32_e32 v245, vcc, 0, v245, vcc
	s_waitcnt vmcnt(6)
	v_pk_add_f32 v[128:129], v[128:129], v[198:199]
	v_pk_add_f32 v[126:127], v[126:127], v[196:197]
	v_pk_add_f32 v[124:125], v[124:125], v[202:203]
	v_pk_add_f32 v[122:123], v[122:123], v[200:201]
	v_mul_f32_e32 v228, 0x3d372713, v126
	v_mul_f32_e32 v229, 0x3d372713, v127
	v_mul_f32_e32 v230, 0x3d372713, v122
	v_mul_f32_e32 v231, 0x3d372713, v123
	v_mul_f32_e32 v232, 0x3d372713, v128
	v_mul_f32_e32 v233, 0x3d372713, v129
	v_mul_f32_e32 v234, 0x3d372713, v124
	v_mul_f32_e32 v235, 0x3d372713, v125
	v_mul_f32_e32 v228, v126, v228
	v_mul_f32_e32 v229, v127, v229
	v_mul_f32_e32 v230, v122, v230
	v_mul_f32_e32 v231, v123, v231
	v_mul_f32_e32 v232, v128, v232
	v_mul_f32_e32 v233, v129, v233
	v_mul_f32_e32 v234, v124, v234
	v_mul_f32_e32 v235, v125, v235
	v_fma_f32 v228, v126, v228, v126
	v_fma_f32 v229, v127, v229, v127
	v_fma_f32 v230, v122, v230, v122
	v_fma_f32 v231, v123, v231, v123
	v_fma_f32 v232, v128, v232, v128
	v_fma_f32 v233, v129, v233, v129
	v_fma_f32 v234, v124, v234, v124
	v_fma_f32 v235, v125, v235, v125
	v_mul_f32_e32 v228, 0xbfcc422a, v228
	v_mul_f32_e32 v229, 0xbfcc422a, v229
	v_mul_f32_e32 v230, 0xbfcc422a, v230
	v_mul_f32_e32 v231, 0xbfcc422a, v231
	v_mul_f32_e32 v232, 0xbfcc422a, v232
	v_mul_f32_e32 v233, 0xbfcc422a, v233
	v_mul_f32_e32 v234, 0xbfcc422a, v234
	v_mul_f32_e32 v235, 0xbfcc422a, v235
	v_mul_f32_e32 v228, 0x3fb8aa3b, v228
	v_mul_f32_e32 v229, 0x3fb8aa3b, v229
	v_mul_f32_e32 v230, 0x3fb8aa3b, v230
	v_mul_f32_e32 v231, 0x3fb8aa3b, v231
	v_mul_f32_e32 v232, 0x3fb8aa3b, v232
	v_mul_f32_e32 v233, 0x3fb8aa3b, v233
	v_mul_f32_e32 v234, 0x3fb8aa3b, v234
	v_mul_f32_e32 v235, 0x3fb8aa3b, v235
	v_exp_f32_e32 v228, v228
	v_exp_f32_e32 v229, v229
	v_exp_f32_e32 v230, v230
	v_exp_f32_e32 v231, v231
	v_exp_f32_e32 v232, v232
	v_exp_f32_e32 v233, v233
	v_exp_f32_e32 v234, v234
	v_exp_f32_e32 v235, v235
	v_add_f32_e32 v228, 1.0, v228
	v_add_f32_e32 v229, 1.0, v229
	v_add_f32_e32 v230, 1.0, v230
	v_add_f32_e32 v231, 1.0, v231
	v_add_f32_e32 v232, 1.0, v232
	v_add_f32_e32 v233, 1.0, v233
	v_add_f32_e32 v234, 1.0, v234
	v_add_f32_e32 v235, 1.0, v235
	v_rcp_f32_e32 v228, v228
	v_rcp_f32_e32 v229, v229
	v_rcp_f32_e32 v230, v230
	v_rcp_f32_e32 v231, v231
	v_rcp_f32_e32 v232, v232
	v_rcp_f32_e32 v233, v233
	v_rcp_f32_e32 v234, v234
	v_rcp_f32_e32 v235, v235
	v_pk_mul_f32 v[126:127], v[126:127], v[228:229]
	v_pk_mul_f32 v[122:123], v[122:123], v[230:231]
	v_pk_mul_f32 v[128:129], v[128:129], v[232:233]
	v_pk_mul_f32 v[124:125], v[124:125], v[234:235]
	v_cvt_pk_bf16_f32 v236, v126, v127
	v_cvt_pk_bf16_f32 v237, v128, v129
	v_cvt_pk_bf16_f32 v238, v122, v123
	v_cvt_pk_bf16_f32 v239, v124, v125
	global_store_dwordx4 v[152:153], v[236:239], off
	global_load_dwordx4 v[196:199], v[244:245], off
	global_load_dwordx4 v[200:203], v[244:245], off offset:16
	s_waitcnt vmcnt(7)
	v_pk_add_f32 v[120:121], v[120:121], v[206:207]
	v_pk_add_f32 v[118:119], v[118:119], v[204:205]
	v_pk_add_f32 v[116:117], v[116:117], v[210:211]
	v_pk_add_f32 v[114:115], v[114:115], v[208:209]
	v_mul_f32_e32 v228, 0x3d372713, v118
	v_mul_f32_e32 v229, 0x3d372713, v119
	v_mul_f32_e32 v230, 0x3d372713, v114
	v_mul_f32_e32 v231, 0x3d372713, v115
	v_mul_f32_e32 v232, 0x3d372713, v120
	v_mul_f32_e32 v233, 0x3d372713, v121
	v_mul_f32_e32 v234, 0x3d372713, v116
	v_mul_f32_e32 v235, 0x3d372713, v117
	v_mul_f32_e32 v228, v118, v228
	v_mul_f32_e32 v229, v119, v229
	v_mul_f32_e32 v230, v114, v230
	v_mul_f32_e32 v231, v115, v231
	v_mul_f32_e32 v232, v120, v232
	v_mul_f32_e32 v233, v121, v233
	v_mul_f32_e32 v234, v116, v234
	v_mul_f32_e32 v235, v117, v235
	v_fma_f32 v228, v118, v228, v118
	v_fma_f32 v229, v119, v229, v119
	v_fma_f32 v230, v114, v230, v114
	v_fma_f32 v231, v115, v231, v115
	v_fma_f32 v232, v120, v232, v120
	v_fma_f32 v233, v121, v233, v121
	v_fma_f32 v234, v116, v234, v116
	v_fma_f32 v235, v117, v235, v117
	v_mul_f32_e32 v228, 0xbfcc422a, v228
	v_mul_f32_e32 v229, 0xbfcc422a, v229
	v_mul_f32_e32 v230, 0xbfcc422a, v230
	v_mul_f32_e32 v231, 0xbfcc422a, v231
	v_mul_f32_e32 v232, 0xbfcc422a, v232
	v_mul_f32_e32 v233, 0xbfcc422a, v233
	v_mul_f32_e32 v234, 0xbfcc422a, v234
	v_mul_f32_e32 v235, 0xbfcc422a, v235
	v_mul_f32_e32 v228, 0x3fb8aa3b, v228
	v_mul_f32_e32 v229, 0x3fb8aa3b, v229
	v_mul_f32_e32 v230, 0x3fb8aa3b, v230
	v_mul_f32_e32 v231, 0x3fb8aa3b, v231
	v_mul_f32_e32 v232, 0x3fb8aa3b, v232
	v_mul_f32_e32 v233, 0x3fb8aa3b, v233
	v_mul_f32_e32 v234, 0x3fb8aa3b, v234
	v_mul_f32_e32 v235, 0x3fb8aa3b, v235
	v_exp_f32_e32 v228, v228
	v_exp_f32_e32 v229, v229
	v_exp_f32_e32 v230, v230
	v_exp_f32_e32 v231, v231
	v_exp_f32_e32 v232, v232
	v_exp_f32_e32 v233, v233
	v_exp_f32_e32 v234, v234
	v_exp_f32_e32 v235, v235
	v_add_f32_e32 v228, 1.0, v228
	v_add_f32_e32 v229, 1.0, v229
	v_add_f32_e32 v230, 1.0, v230
	v_add_f32_e32 v231, 1.0, v231
	v_add_f32_e32 v232, 1.0, v232
	v_add_f32_e32 v233, 1.0, v233
	v_add_f32_e32 v234, 1.0, v234
	v_add_f32_e32 v235, 1.0, v235
	v_rcp_f32_e32 v228, v228
	v_rcp_f32_e32 v229, v229
	v_rcp_f32_e32 v230, v230
	v_rcp_f32_e32 v231, v231
	v_rcp_f32_e32 v232, v232
	v_rcp_f32_e32 v233, v233
	v_rcp_f32_e32 v234, v234
	v_rcp_f32_e32 v235, v235
	v_pk_mul_f32 v[118:119], v[118:119], v[228:229]
	v_pk_mul_f32 v[114:115], v[114:115], v[230:231]
	v_pk_mul_f32 v[120:121], v[120:121], v[232:233]
	v_pk_mul_f32 v[116:117], v[116:117], v[234:235]
	v_cvt_pk_bf16_f32 v236, v118, v119
	v_cvt_pk_bf16_f32 v237, v120, v121
	v_cvt_pk_bf16_f32 v238, v114, v115
	v_cvt_pk_bf16_f32 v239, v116, v117
	global_store_dwordx4 v[246:247], v[236:239], off
	v_add_co_u32_e32 v152, vcc, 0x40000, v152
	s_nop 1
	v_addc_co_u32_e32 v153, vcc, 0, v153, vcc
	v_add_co_u32_e32 v246, vcc, 0x40000, v246
	s_nop 1
	v_addc_co_u32_e32 v247, vcc, 0, v247, vcc
	global_load_dwordx4 v[204:207], v[244:245], off offset:512
	global_load_dwordx4 v[208:211], v[244:245], off offset:528
	v_add_co_u32_e32 v244, vcc, 0x4000, v244
	s_nop 1
	v_addc_co_u32_e32 v245, vcc, 0, v245, vcc
	s_waitcnt vmcnt(8)
	v_pk_add_f32 v[112:113], v[112:113], v[214:215]
	v_pk_add_f32 v[110:111], v[110:111], v[212:213]
	v_pk_add_f32 v[108:109], v[108:109], v[218:219]
	v_pk_add_f32 v[106:107], v[106:107], v[216:217]
	v_mul_f32_e32 v228, 0x3d372713, v110
	v_mul_f32_e32 v229, 0x3d372713, v111
	v_mul_f32_e32 v230, 0x3d372713, v106
	v_mul_f32_e32 v231, 0x3d372713, v107
	v_mul_f32_e32 v232, 0x3d372713, v112
	v_mul_f32_e32 v233, 0x3d372713, v113
	v_mul_f32_e32 v234, 0x3d372713, v108
	v_mul_f32_e32 v235, 0x3d372713, v109
	v_mul_f32_e32 v228, v110, v228
	v_mul_f32_e32 v229, v111, v229
	v_mul_f32_e32 v230, v106, v230
	v_mul_f32_e32 v231, v107, v231
	v_mul_f32_e32 v232, v112, v232
	v_mul_f32_e32 v233, v113, v233
	v_mul_f32_e32 v234, v108, v234
	v_mul_f32_e32 v235, v109, v235
	v_fma_f32 v228, v110, v228, v110
	v_fma_f32 v229, v111, v229, v111
	v_fma_f32 v230, v106, v230, v106
	v_fma_f32 v231, v107, v231, v107
	v_fma_f32 v232, v112, v232, v112
	v_fma_f32 v233, v113, v233, v113
	v_fma_f32 v234, v108, v234, v108
	v_fma_f32 v235, v109, v235, v109
	v_mul_f32_e32 v228, 0xbfcc422a, v228
	v_mul_f32_e32 v229, 0xbfcc422a, v229
	v_mul_f32_e32 v230, 0xbfcc422a, v230
	v_mul_f32_e32 v231, 0xbfcc422a, v231
	v_mul_f32_e32 v232, 0xbfcc422a, v232
	v_mul_f32_e32 v233, 0xbfcc422a, v233
	v_mul_f32_e32 v234, 0xbfcc422a, v234
	v_mul_f32_e32 v235, 0xbfcc422a, v235
	v_mul_f32_e32 v228, 0x3fb8aa3b, v228
	v_mul_f32_e32 v229, 0x3fb8aa3b, v229
	v_mul_f32_e32 v230, 0x3fb8aa3b, v230
	v_mul_f32_e32 v231, 0x3fb8aa3b, v231
	v_mul_f32_e32 v232, 0x3fb8aa3b, v232
	v_mul_f32_e32 v233, 0x3fb8aa3b, v233
	v_mul_f32_e32 v234, 0x3fb8aa3b, v234
	v_mul_f32_e32 v235, 0x3fb8aa3b, v235
	v_exp_f32_e32 v228, v228
	v_exp_f32_e32 v229, v229
	v_exp_f32_e32 v230, v230
	v_exp_f32_e32 v231, v231
	v_exp_f32_e32 v232, v232
	v_exp_f32_e32 v233, v233
	v_exp_f32_e32 v234, v234
	v_exp_f32_e32 v235, v235
	v_add_f32_e32 v228, 1.0, v228
	v_add_f32_e32 v229, 1.0, v229
	v_add_f32_e32 v230, 1.0, v230
	v_add_f32_e32 v231, 1.0, v231
	v_add_f32_e32 v232, 1.0, v232
	v_add_f32_e32 v233, 1.0, v233
	v_add_f32_e32 v234, 1.0, v234
	v_add_f32_e32 v235, 1.0, v235
	v_rcp_f32_e32 v228, v228
	v_rcp_f32_e32 v229, v229
	v_rcp_f32_e32 v230, v230
	v_rcp_f32_e32 v231, v231
	v_rcp_f32_e32 v232, v232
	v_rcp_f32_e32 v233, v233
	v_rcp_f32_e32 v234, v234
	v_rcp_f32_e32 v235, v235
	v_pk_mul_f32 v[110:111], v[110:111], v[228:229]
	v_pk_mul_f32 v[106:107], v[106:107], v[230:231]
	v_pk_mul_f32 v[112:113], v[112:113], v[232:233]
	v_pk_mul_f32 v[108:109], v[108:109], v[234:235]
	v_cvt_pk_bf16_f32 v236, v110, v111
	v_cvt_pk_bf16_f32 v237, v112, v113
	v_cvt_pk_bf16_f32 v238, v106, v107
	v_cvt_pk_bf16_f32 v239, v108, v109
	global_store_dwordx4 v[152:153], v[236:239], off
	global_load_dwordx4 v[212:215], v[244:245], off
	global_load_dwordx4 v[216:219], v[244:245], off offset:16
	s_waitcnt vmcnt(9)
	v_pk_add_f32 v[104:105], v[104:105], v[222:223]
	v_pk_add_f32 v[102:103], v[102:103], v[220:221]
	v_pk_add_f32 v[100:101], v[100:101], v[226:227]
	v_pk_add_f32 v[98:99], v[98:99], v[224:225]
	v_mul_f32_e32 v228, 0x3d372713, v102
	v_mul_f32_e32 v229, 0x3d372713, v103
	v_mul_f32_e32 v230, 0x3d372713, v98
	v_mul_f32_e32 v231, 0x3d372713, v99
	v_mul_f32_e32 v232, 0x3d372713, v104
	v_mul_f32_e32 v233, 0x3d372713, v105
	v_mul_f32_e32 v234, 0x3d372713, v100
	v_mul_f32_e32 v235, 0x3d372713, v101
	v_mul_f32_e32 v228, v102, v228
	v_mul_f32_e32 v229, v103, v229
	v_mul_f32_e32 v230, v98, v230
	v_mul_f32_e32 v231, v99, v231
	v_mul_f32_e32 v232, v104, v232
	v_mul_f32_e32 v233, v105, v233
	v_mul_f32_e32 v234, v100, v234
	v_mul_f32_e32 v235, v101, v235
	v_fma_f32 v228, v102, v228, v102
	v_fma_f32 v229, v103, v229, v103
	v_fma_f32 v230, v98, v230, v98
	v_fma_f32 v231, v99, v231, v99
	v_fma_f32 v232, v104, v232, v104
	v_fma_f32 v233, v105, v233, v105
	v_fma_f32 v234, v100, v234, v100
	v_fma_f32 v235, v101, v235, v101
	v_mul_f32_e32 v228, 0xbfcc422a, v228
	v_mul_f32_e32 v229, 0xbfcc422a, v229
	v_mul_f32_e32 v230, 0xbfcc422a, v230
	v_mul_f32_e32 v231, 0xbfcc422a, v231
	v_mul_f32_e32 v232, 0xbfcc422a, v232
	v_mul_f32_e32 v233, 0xbfcc422a, v233
	v_mul_f32_e32 v234, 0xbfcc422a, v234
	v_mul_f32_e32 v235, 0xbfcc422a, v235
	v_mul_f32_e32 v228, 0x3fb8aa3b, v228
	v_mul_f32_e32 v229, 0x3fb8aa3b, v229
	v_mul_f32_e32 v230, 0x3fb8aa3b, v230
	v_mul_f32_e32 v231, 0x3fb8aa3b, v231
	v_mul_f32_e32 v232, 0x3fb8aa3b, v232
	v_mul_f32_e32 v233, 0x3fb8aa3b, v233
	v_mul_f32_e32 v234, 0x3fb8aa3b, v234
	v_mul_f32_e32 v235, 0x3fb8aa3b, v235
	v_exp_f32_e32 v228, v228
	v_exp_f32_e32 v229, v229
	v_exp_f32_e32 v230, v230
	v_exp_f32_e32 v231, v231
	v_exp_f32_e32 v232, v232
	v_exp_f32_e32 v233, v233
	v_exp_f32_e32 v234, v234
	v_exp_f32_e32 v235, v235
	v_add_f32_e32 v228, 1.0, v228
	v_add_f32_e32 v229, 1.0, v229
	v_add_f32_e32 v230, 1.0, v230
	v_add_f32_e32 v231, 1.0, v231
	v_add_f32_e32 v232, 1.0, v232
	v_add_f32_e32 v233, 1.0, v233
	v_add_f32_e32 v234, 1.0, v234
	v_add_f32_e32 v235, 1.0, v235
	v_rcp_f32_e32 v228, v228
	v_rcp_f32_e32 v229, v229
	v_rcp_f32_e32 v230, v230
	v_rcp_f32_e32 v231, v231
	v_rcp_f32_e32 v232, v232
	v_rcp_f32_e32 v233, v233
	v_rcp_f32_e32 v234, v234
	v_rcp_f32_e32 v235, v235
	v_pk_mul_f32 v[102:103], v[102:103], v[228:229]
	v_pk_mul_f32 v[98:99], v[98:99], v[230:231]
	v_pk_mul_f32 v[104:105], v[104:105], v[232:233]
	v_pk_mul_f32 v[100:101], v[100:101], v[234:235]
	v_cvt_pk_bf16_f32 v236, v102, v103
	v_cvt_pk_bf16_f32 v237, v104, v105
	v_cvt_pk_bf16_f32 v238, v98, v99
	v_cvt_pk_bf16_f32 v239, v100, v101
	global_store_dwordx4 v[246:247], v[236:239], off
	v_add_co_u32_e32 v152, vcc, 0x40000, v152
	s_nop 1
	v_addc_co_u32_e32 v153, vcc, 0, v153, vcc
	v_add_co_u32_e32 v246, vcc, 0x40000, v246
	s_nop 1
	v_addc_co_u32_e32 v247, vcc, 0, v247, vcc
	global_load_dwordx4 v[220:223], v[244:245], off offset:512
	global_load_dwordx4 v[224:227], v[244:245], off offset:528
	v_add_co_u32_e32 v244, vcc, 0x14000, v244
	s_nop 1
	v_addc_co_u32_e32 v245, vcc, 0, v245, vcc
	s_waitcnt vmcnt(9)
	v_pk_add_f32 v[96:97], v[96:97], v[198:199]
	v_pk_add_f32 v[94:95], v[94:95], v[196:197]
	v_pk_add_f32 v[92:93], v[92:93], v[202:203]
	v_pk_add_f32 v[90:91], v[90:91], v[200:201]
	v_mul_f32_e32 v228, 0x3d372713, v94
	v_mul_f32_e32 v229, 0x3d372713, v95
	v_mul_f32_e32 v230, 0x3d372713, v90
	v_mul_f32_e32 v231, 0x3d372713, v91
	v_mul_f32_e32 v232, 0x3d372713, v96
	v_mul_f32_e32 v233, 0x3d372713, v97
	v_mul_f32_e32 v234, 0x3d372713, v92
	v_mul_f32_e32 v235, 0x3d372713, v93
	v_mul_f32_e32 v228, v94, v228
	v_mul_f32_e32 v229, v95, v229
	v_mul_f32_e32 v230, v90, v230
	v_mul_f32_e32 v231, v91, v231
	v_mul_f32_e32 v232, v96, v232
	v_mul_f32_e32 v233, v97, v233
	v_mul_f32_e32 v234, v92, v234
	v_mul_f32_e32 v235, v93, v235
	v_fma_f32 v228, v94, v228, v94
	v_fma_f32 v229, v95, v229, v95
	v_fma_f32 v230, v90, v230, v90
	v_fma_f32 v231, v91, v231, v91
	v_fma_f32 v232, v96, v232, v96
	v_fma_f32 v233, v97, v233, v97
	v_fma_f32 v234, v92, v234, v92
	v_fma_f32 v235, v93, v235, v93
	v_mul_f32_e32 v228, 0xbfcc422a, v228
	v_mul_f32_e32 v229, 0xbfcc422a, v229
	v_mul_f32_e32 v230, 0xbfcc422a, v230
	v_mul_f32_e32 v231, 0xbfcc422a, v231
	v_mul_f32_e32 v232, 0xbfcc422a, v232
	v_mul_f32_e32 v233, 0xbfcc422a, v233
	v_mul_f32_e32 v234, 0xbfcc422a, v234
	v_mul_f32_e32 v235, 0xbfcc422a, v235
	v_mul_f32_e32 v228, 0x3fb8aa3b, v228
	v_mul_f32_e32 v229, 0x3fb8aa3b, v229
	v_mul_f32_e32 v230, 0x3fb8aa3b, v230
	v_mul_f32_e32 v231, 0x3fb8aa3b, v231
	v_mul_f32_e32 v232, 0x3fb8aa3b, v232
	v_mul_f32_e32 v233, 0x3fb8aa3b, v233
	v_mul_f32_e32 v234, 0x3fb8aa3b, v234
	v_mul_f32_e32 v235, 0x3fb8aa3b, v235
	v_exp_f32_e32 v228, v228
	v_exp_f32_e32 v229, v229
	v_exp_f32_e32 v230, v230
	v_exp_f32_e32 v231, v231
	v_exp_f32_e32 v232, v232
	v_exp_f32_e32 v233, v233
	v_exp_f32_e32 v234, v234
	v_exp_f32_e32 v235, v235
	v_add_f32_e32 v228, 1.0, v228
	v_add_f32_e32 v229, 1.0, v229
	v_add_f32_e32 v230, 1.0, v230
	v_add_f32_e32 v231, 1.0, v231
	v_add_f32_e32 v232, 1.0, v232
	v_add_f32_e32 v233, 1.0, v233
	v_add_f32_e32 v234, 1.0, v234
	v_add_f32_e32 v235, 1.0, v235
	v_rcp_f32_e32 v228, v228
	v_rcp_f32_e32 v229, v229
	v_rcp_f32_e32 v230, v230
	v_rcp_f32_e32 v231, v231
	v_rcp_f32_e32 v232, v232
	v_rcp_f32_e32 v233, v233
	v_rcp_f32_e32 v234, v234
	v_rcp_f32_e32 v235, v235
	v_pk_mul_f32 v[94:95], v[94:95], v[228:229]
	v_pk_mul_f32 v[90:91], v[90:91], v[230:231]
	v_pk_mul_f32 v[96:97], v[96:97], v[232:233]
	v_pk_mul_f32 v[92:93], v[92:93], v[234:235]
	v_cvt_pk_bf16_f32 v236, v94, v95
	v_cvt_pk_bf16_f32 v237, v96, v97
	v_cvt_pk_bf16_f32 v238, v90, v91
	v_cvt_pk_bf16_f32 v239, v92, v93
	global_store_dwordx4 v[152:153], v[236:239], off
	global_load_dwordx4 v[196:199], v[244:245], off
	global_load_dwordx4 v[200:203], v[244:245], off offset:16
	s_waitcnt vmcnt(9)
	v_pk_add_f32 v[88:89], v[88:89], v[206:207]
	v_pk_add_f32 v[86:87], v[86:87], v[204:205]
	v_pk_add_f32 v[84:85], v[84:85], v[210:211]
	v_pk_add_f32 v[82:83], v[82:83], v[208:209]
	v_mul_f32_e32 v228, 0x3d372713, v86
	v_mul_f32_e32 v229, 0x3d372713, v87
	v_mul_f32_e32 v230, 0x3d372713, v82
	v_mul_f32_e32 v231, 0x3d372713, v83
	v_mul_f32_e32 v232, 0x3d372713, v88
	v_mul_f32_e32 v233, 0x3d372713, v89
	v_mul_f32_e32 v234, 0x3d372713, v84
	v_mul_f32_e32 v235, 0x3d372713, v85
	v_mul_f32_e32 v228, v86, v228
	v_mul_f32_e32 v229, v87, v229
	v_mul_f32_e32 v230, v82, v230
	v_mul_f32_e32 v231, v83, v231
	v_mul_f32_e32 v232, v88, v232
	v_mul_f32_e32 v233, v89, v233
	v_mul_f32_e32 v234, v84, v234
	v_mul_f32_e32 v235, v85, v235
	v_fma_f32 v228, v86, v228, v86
	v_fma_f32 v229, v87, v229, v87
	v_fma_f32 v230, v82, v230, v82
	v_fma_f32 v231, v83, v231, v83
	v_fma_f32 v232, v88, v232, v88
	v_fma_f32 v233, v89, v233, v89
	v_fma_f32 v234, v84, v234, v84
	v_fma_f32 v235, v85, v235, v85
	v_mul_f32_e32 v228, 0xbfcc422a, v228
	v_mul_f32_e32 v229, 0xbfcc422a, v229
	v_mul_f32_e32 v230, 0xbfcc422a, v230
	v_mul_f32_e32 v231, 0xbfcc422a, v231
	v_mul_f32_e32 v232, 0xbfcc422a, v232
	v_mul_f32_e32 v233, 0xbfcc422a, v233
	v_mul_f32_e32 v234, 0xbfcc422a, v234
	v_mul_f32_e32 v235, 0xbfcc422a, v235
	v_mul_f32_e32 v228, 0x3fb8aa3b, v228
	v_mul_f32_e32 v229, 0x3fb8aa3b, v229
	v_mul_f32_e32 v230, 0x3fb8aa3b, v230
	v_mul_f32_e32 v231, 0x3fb8aa3b, v231
	v_mul_f32_e32 v232, 0x3fb8aa3b, v232
	v_mul_f32_e32 v233, 0x3fb8aa3b, v233
	v_mul_f32_e32 v234, 0x3fb8aa3b, v234
	v_mul_f32_e32 v235, 0x3fb8aa3b, v235
	v_exp_f32_e32 v228, v228
	v_exp_f32_e32 v229, v229
	v_exp_f32_e32 v230, v230
	v_exp_f32_e32 v231, v231
	v_exp_f32_e32 v232, v232
	v_exp_f32_e32 v233, v233
	v_exp_f32_e32 v234, v234
	v_exp_f32_e32 v235, v235
	v_add_f32_e32 v228, 1.0, v228
	v_add_f32_e32 v229, 1.0, v229
	v_add_f32_e32 v230, 1.0, v230
	v_add_f32_e32 v231, 1.0, v231
	v_add_f32_e32 v232, 1.0, v232
	v_add_f32_e32 v233, 1.0, v233
	v_add_f32_e32 v234, 1.0, v234
	v_add_f32_e32 v235, 1.0, v235
	v_rcp_f32_e32 v228, v228
	v_rcp_f32_e32 v229, v229
	v_rcp_f32_e32 v230, v230
	v_rcp_f32_e32 v231, v231
	v_rcp_f32_e32 v232, v232
	v_rcp_f32_e32 v233, v233
	v_rcp_f32_e32 v234, v234
	v_rcp_f32_e32 v235, v235
	v_pk_mul_f32 v[86:87], v[86:87], v[228:229]
	v_pk_mul_f32 v[82:83], v[82:83], v[230:231]
	v_pk_mul_f32 v[88:89], v[88:89], v[232:233]
	v_pk_mul_f32 v[84:85], v[84:85], v[234:235]
	v_cvt_pk_bf16_f32 v236, v86, v87
	v_cvt_pk_bf16_f32 v237, v88, v89
	v_cvt_pk_bf16_f32 v238, v82, v83
	v_cvt_pk_bf16_f32 v239, v84, v85
	global_store_dwordx4 v[246:247], v[236:239], off
	v_add_co_u32_e32 v152, vcc, 0x40000, v152
	s_nop 1
	v_addc_co_u32_e32 v153, vcc, 0, v153, vcc
	v_add_co_u32_e32 v246, vcc, 0x40000, v246
	s_nop 1
	v_addc_co_u32_e32 v247, vcc, 0, v247, vcc
	global_load_dwordx4 v[204:207], v[244:245], off offset:512
	global_load_dwordx4 v[208:211], v[244:245], off offset:528
	v_add_co_u32_e32 v244, vcc, 0x4000, v244
	s_nop 1
	v_addc_co_u32_e32 v245, vcc, 0, v245, vcc
	s_waitcnt vmcnt(9)
	v_pk_add_f32 v[80:81], v[80:81], v[214:215]
	v_pk_add_f32 v[78:79], v[78:79], v[212:213]
	v_pk_add_f32 v[76:77], v[76:77], v[218:219]
	v_pk_add_f32 v[74:75], v[74:75], v[216:217]
	v_mul_f32_e32 v228, 0x3d372713, v78
	v_mul_f32_e32 v229, 0x3d372713, v79
	v_mul_f32_e32 v230, 0x3d372713, v74
	v_mul_f32_e32 v231, 0x3d372713, v75
	v_mul_f32_e32 v232, 0x3d372713, v80
	v_mul_f32_e32 v233, 0x3d372713, v81
	v_mul_f32_e32 v234, 0x3d372713, v76
	v_mul_f32_e32 v235, 0x3d372713, v77
	v_mul_f32_e32 v228, v78, v228
	v_mul_f32_e32 v229, v79, v229
	v_mul_f32_e32 v230, v74, v230
	v_mul_f32_e32 v231, v75, v231
	v_mul_f32_e32 v232, v80, v232
	v_mul_f32_e32 v233, v81, v233
	v_mul_f32_e32 v234, v76, v234
	v_mul_f32_e32 v235, v77, v235
	v_fma_f32 v228, v78, v228, v78
	v_fma_f32 v229, v79, v229, v79
	v_fma_f32 v230, v74, v230, v74
	v_fma_f32 v231, v75, v231, v75
	v_fma_f32 v232, v80, v232, v80
	v_fma_f32 v233, v81, v233, v81
	v_fma_f32 v234, v76, v234, v76
	v_fma_f32 v235, v77, v235, v77
	v_mul_f32_e32 v228, 0xbfcc422a, v228
	v_mul_f32_e32 v229, 0xbfcc422a, v229
	v_mul_f32_e32 v230, 0xbfcc422a, v230
	v_mul_f32_e32 v231, 0xbfcc422a, v231
	v_mul_f32_e32 v232, 0xbfcc422a, v232
	v_mul_f32_e32 v233, 0xbfcc422a, v233
	v_mul_f32_e32 v234, 0xbfcc422a, v234
	v_mul_f32_e32 v235, 0xbfcc422a, v235
	v_mul_f32_e32 v228, 0x3fb8aa3b, v228
	v_mul_f32_e32 v229, 0x3fb8aa3b, v229
	v_mul_f32_e32 v230, 0x3fb8aa3b, v230
	v_mul_f32_e32 v231, 0x3fb8aa3b, v231
	v_mul_f32_e32 v232, 0x3fb8aa3b, v232
	v_mul_f32_e32 v233, 0x3fb8aa3b, v233
	v_mul_f32_e32 v234, 0x3fb8aa3b, v234
	v_mul_f32_e32 v235, 0x3fb8aa3b, v235
	v_exp_f32_e32 v228, v228
	v_exp_f32_e32 v229, v229
	v_exp_f32_e32 v230, v230
	v_exp_f32_e32 v231, v231
	v_exp_f32_e32 v232, v232
	v_exp_f32_e32 v233, v233
	v_exp_f32_e32 v234, v234
	v_exp_f32_e32 v235, v235
	v_add_f32_e32 v228, 1.0, v228
	v_add_f32_e32 v229, 1.0, v229
	v_add_f32_e32 v230, 1.0, v230
	v_add_f32_e32 v231, 1.0, v231
	v_add_f32_e32 v232, 1.0, v232
	v_add_f32_e32 v233, 1.0, v233
	v_add_f32_e32 v234, 1.0, v234
	v_add_f32_e32 v235, 1.0, v235
	v_rcp_f32_e32 v228, v228
	v_rcp_f32_e32 v229, v229
	v_rcp_f32_e32 v230, v230
	v_rcp_f32_e32 v231, v231
	v_rcp_f32_e32 v232, v232
	v_rcp_f32_e32 v233, v233
	v_rcp_f32_e32 v234, v234
	v_rcp_f32_e32 v235, v235
	v_pk_mul_f32 v[78:79], v[78:79], v[228:229]
	v_pk_mul_f32 v[74:75], v[74:75], v[230:231]
	v_pk_mul_f32 v[80:81], v[80:81], v[232:233]
	v_pk_mul_f32 v[76:77], v[76:77], v[234:235]
	v_cvt_pk_bf16_f32 v236, v78, v79
	v_cvt_pk_bf16_f32 v237, v80, v81
	v_cvt_pk_bf16_f32 v238, v74, v75
	v_cvt_pk_bf16_f32 v239, v76, v77
	global_store_dwordx4 v[152:153], v[236:239], off
	global_load_dwordx4 v[212:215], v[244:245], off
	global_load_dwordx4 v[216:219], v[244:245], off offset:16
	s_waitcnt vmcnt(9)
	v_pk_add_f32 v[72:73], v[72:73], v[222:223]
	v_pk_add_f32 v[70:71], v[70:71], v[220:221]
	v_pk_add_f32 v[68:69], v[68:69], v[226:227]
	v_pk_add_f32 v[66:67], v[66:67], v[224:225]
	v_mul_f32_e32 v228, 0x3d372713, v70
	v_mul_f32_e32 v229, 0x3d372713, v71
	v_mul_f32_e32 v230, 0x3d372713, v66
	v_mul_f32_e32 v231, 0x3d372713, v67
	v_mul_f32_e32 v232, 0x3d372713, v72
	v_mul_f32_e32 v233, 0x3d372713, v73
	v_mul_f32_e32 v234, 0x3d372713, v68
	v_mul_f32_e32 v235, 0x3d372713, v69
	v_mul_f32_e32 v228, v70, v228
	v_mul_f32_e32 v229, v71, v229
	v_mul_f32_e32 v230, v66, v230
	v_mul_f32_e32 v231, v67, v231
	v_mul_f32_e32 v232, v72, v232
	v_mul_f32_e32 v233, v73, v233
	v_mul_f32_e32 v234, v68, v234
	v_mul_f32_e32 v235, v69, v235
	v_fma_f32 v228, v70, v228, v70
	v_fma_f32 v229, v71, v229, v71
	v_fma_f32 v230, v66, v230, v66
	v_fma_f32 v231, v67, v231, v67
	v_fma_f32 v232, v72, v232, v72
	v_fma_f32 v233, v73, v233, v73
	v_fma_f32 v234, v68, v234, v68
	v_fma_f32 v235, v69, v235, v69
	v_mul_f32_e32 v228, 0xbfcc422a, v228
	v_mul_f32_e32 v229, 0xbfcc422a, v229
	v_mul_f32_e32 v230, 0xbfcc422a, v230
	v_mul_f32_e32 v231, 0xbfcc422a, v231
	v_mul_f32_e32 v232, 0xbfcc422a, v232
	v_mul_f32_e32 v233, 0xbfcc422a, v233
	v_mul_f32_e32 v234, 0xbfcc422a, v234
	v_mul_f32_e32 v235, 0xbfcc422a, v235
	v_mul_f32_e32 v228, 0x3fb8aa3b, v228
	v_mul_f32_e32 v229, 0x3fb8aa3b, v229
	v_mul_f32_e32 v230, 0x3fb8aa3b, v230
	v_mul_f32_e32 v231, 0x3fb8aa3b, v231
	v_mul_f32_e32 v232, 0x3fb8aa3b, v232
	v_mul_f32_e32 v233, 0x3fb8aa3b, v233
	v_mul_f32_e32 v234, 0x3fb8aa3b, v234
	v_mul_f32_e32 v235, 0x3fb8aa3b, v235
	v_exp_f32_e32 v228, v228
	v_exp_f32_e32 v229, v229
	v_exp_f32_e32 v230, v230
	v_exp_f32_e32 v231, v231
	v_exp_f32_e32 v232, v232
	v_exp_f32_e32 v233, v233
	v_exp_f32_e32 v234, v234
	v_exp_f32_e32 v235, v235
	v_add_f32_e32 v228, 1.0, v228
	v_add_f32_e32 v229, 1.0, v229
	v_add_f32_e32 v230, 1.0, v230
	v_add_f32_e32 v231, 1.0, v231
	v_add_f32_e32 v232, 1.0, v232
	v_add_f32_e32 v233, 1.0, v233
	v_add_f32_e32 v234, 1.0, v234
	v_add_f32_e32 v235, 1.0, v235
	v_rcp_f32_e32 v228, v228
	v_rcp_f32_e32 v229, v229
	v_rcp_f32_e32 v230, v230
	v_rcp_f32_e32 v231, v231
	v_rcp_f32_e32 v232, v232
	v_rcp_f32_e32 v233, v233
	v_rcp_f32_e32 v234, v234
	v_rcp_f32_e32 v235, v235
	v_pk_mul_f32 v[70:71], v[70:71], v[228:229]
	v_pk_mul_f32 v[66:67], v[66:67], v[230:231]
	v_pk_mul_f32 v[72:73], v[72:73], v[232:233]
	v_pk_mul_f32 v[68:69], v[68:69], v[234:235]
	v_cvt_pk_bf16_f32 v236, v70, v71
	v_cvt_pk_bf16_f32 v237, v72, v73
	v_cvt_pk_bf16_f32 v238, v66, v67
	v_cvt_pk_bf16_f32 v239, v68, v69
	global_store_dwordx4 v[246:247], v[236:239], off
	v_add_co_u32_e32 v152, vcc, 0x140000, v152
	s_nop 1
	v_addc_co_u32_e32 v153, vcc, 0, v153, vcc
	v_add_co_u32_e32 v246, vcc, 0x140000, v246
	s_nop 1
	v_addc_co_u32_e32 v247, vcc, 0, v247, vcc
	global_load_dwordx4 v[220:223], v[244:245], off offset:512
	global_load_dwordx4 v[224:227], v[244:245], off offset:528
	v_add_co_u32_e32 v244, vcc, 0x4000, v244
	s_nop 1
	v_addc_co_u32_e32 v245, vcc, 0, v245, vcc
	s_waitcnt vmcnt(9)
	v_pk_add_f32 v[64:65], v[64:65], v[198:199]
	v_pk_add_f32 v[62:63], v[62:63], v[196:197]
	v_pk_add_f32 v[60:61], v[60:61], v[202:203]
	v_pk_add_f32 v[58:59], v[58:59], v[200:201]
	v_mul_f32_e32 v228, 0x3d372713, v62
	v_mul_f32_e32 v229, 0x3d372713, v63
	v_mul_f32_e32 v230, 0x3d372713, v58
	v_mul_f32_e32 v231, 0x3d372713, v59
	v_mul_f32_e32 v232, 0x3d372713, v64
	v_mul_f32_e32 v233, 0x3d372713, v65
	v_mul_f32_e32 v234, 0x3d372713, v60
	v_mul_f32_e32 v235, 0x3d372713, v61
	v_mul_f32_e32 v228, v62, v228
	v_mul_f32_e32 v229, v63, v229
	v_mul_f32_e32 v230, v58, v230
	v_mul_f32_e32 v231, v59, v231
	v_mul_f32_e32 v232, v64, v232
	v_mul_f32_e32 v233, v65, v233
	v_mul_f32_e32 v234, v60, v234
	v_mul_f32_e32 v235, v61, v235
	v_fma_f32 v228, v62, v228, v62
	v_fma_f32 v229, v63, v229, v63
	v_fma_f32 v230, v58, v230, v58
	v_fma_f32 v231, v59, v231, v59
	v_fma_f32 v232, v64, v232, v64
	v_fma_f32 v233, v65, v233, v65
	v_fma_f32 v234, v60, v234, v60
	v_fma_f32 v235, v61, v235, v61
	v_mul_f32_e32 v228, 0xbfcc422a, v228
	v_mul_f32_e32 v229, 0xbfcc422a, v229
	v_mul_f32_e32 v230, 0xbfcc422a, v230
	v_mul_f32_e32 v231, 0xbfcc422a, v231
	v_mul_f32_e32 v232, 0xbfcc422a, v232
	v_mul_f32_e32 v233, 0xbfcc422a, v233
	v_mul_f32_e32 v234, 0xbfcc422a, v234
	v_mul_f32_e32 v235, 0xbfcc422a, v235
	v_mul_f32_e32 v228, 0x3fb8aa3b, v228
	v_mul_f32_e32 v229, 0x3fb8aa3b, v229
	v_mul_f32_e32 v230, 0x3fb8aa3b, v230
	v_mul_f32_e32 v231, 0x3fb8aa3b, v231
	v_mul_f32_e32 v232, 0x3fb8aa3b, v232
	v_mul_f32_e32 v233, 0x3fb8aa3b, v233
	v_mul_f32_e32 v234, 0x3fb8aa3b, v234
	v_mul_f32_e32 v235, 0x3fb8aa3b, v235
	v_exp_f32_e32 v228, v228
	v_exp_f32_e32 v229, v229
	v_exp_f32_e32 v230, v230
	v_exp_f32_e32 v231, v231
	v_exp_f32_e32 v232, v232
	v_exp_f32_e32 v233, v233
	v_exp_f32_e32 v234, v234
	v_exp_f32_e32 v235, v235
	v_add_f32_e32 v228, 1.0, v228
	v_add_f32_e32 v229, 1.0, v229
	v_add_f32_e32 v230, 1.0, v230
	v_add_f32_e32 v231, 1.0, v231
	v_add_f32_e32 v232, 1.0, v232
	v_add_f32_e32 v233, 1.0, v233
	v_add_f32_e32 v234, 1.0, v234
	v_add_f32_e32 v235, 1.0, v235
	v_rcp_f32_e32 v228, v228
	v_rcp_f32_e32 v229, v229
	v_rcp_f32_e32 v230, v230
	v_rcp_f32_e32 v231, v231
	v_rcp_f32_e32 v232, v232
	v_rcp_f32_e32 v233, v233
	v_rcp_f32_e32 v234, v234
	v_rcp_f32_e32 v235, v235
	v_pk_mul_f32 v[62:63], v[62:63], v[228:229]
	v_pk_mul_f32 v[58:59], v[58:59], v[230:231]
	v_pk_mul_f32 v[64:65], v[64:65], v[232:233]
	v_pk_mul_f32 v[60:61], v[60:61], v[234:235]
	v_cvt_pk_bf16_f32 v236, v62, v63
	v_cvt_pk_bf16_f32 v237, v64, v65
	v_cvt_pk_bf16_f32 v238, v58, v59
	v_cvt_pk_bf16_f32 v239, v60, v61
	global_store_dwordx4 v[152:153], v[236:239], off
	global_load_dwordx4 v[196:199], v[244:245], off
	global_load_dwordx4 v[200:203], v[244:245], off offset:16
	s_waitcnt vmcnt(9)
	v_pk_add_f32 v[56:57], v[56:57], v[206:207]
	v_pk_add_f32 v[54:55], v[54:55], v[204:205]
	v_pk_add_f32 v[52:53], v[52:53], v[210:211]
	v_pk_add_f32 v[50:51], v[50:51], v[208:209]
	v_mul_f32_e32 v228, 0x3d372713, v54
	v_mul_f32_e32 v229, 0x3d372713, v55
	v_mul_f32_e32 v230, 0x3d372713, v50
	v_mul_f32_e32 v231, 0x3d372713, v51
	v_mul_f32_e32 v232, 0x3d372713, v56
	v_mul_f32_e32 v233, 0x3d372713, v57
	v_mul_f32_e32 v234, 0x3d372713, v52
	v_mul_f32_e32 v235, 0x3d372713, v53
	v_mul_f32_e32 v228, v54, v228
	v_mul_f32_e32 v229, v55, v229
	v_mul_f32_e32 v230, v50, v230
	v_mul_f32_e32 v231, v51, v231
	v_mul_f32_e32 v232, v56, v232
	v_mul_f32_e32 v233, v57, v233
	v_mul_f32_e32 v234, v52, v234
	v_mul_f32_e32 v235, v53, v235
	v_fma_f32 v228, v54, v228, v54
	v_fma_f32 v229, v55, v229, v55
	v_fma_f32 v230, v50, v230, v50
	v_fma_f32 v231, v51, v231, v51
	v_fma_f32 v232, v56, v232, v56
	v_fma_f32 v233, v57, v233, v57
	v_fma_f32 v234, v52, v234, v52
	v_fma_f32 v235, v53, v235, v53
	v_mul_f32_e32 v228, 0xbfcc422a, v228
	v_mul_f32_e32 v229, 0xbfcc422a, v229
	v_mul_f32_e32 v230, 0xbfcc422a, v230
	v_mul_f32_e32 v231, 0xbfcc422a, v231
	v_mul_f32_e32 v232, 0xbfcc422a, v232
	v_mul_f32_e32 v233, 0xbfcc422a, v233
	v_mul_f32_e32 v234, 0xbfcc422a, v234
	v_mul_f32_e32 v235, 0xbfcc422a, v235
	v_mul_f32_e32 v228, 0x3fb8aa3b, v228
	v_mul_f32_e32 v229, 0x3fb8aa3b, v229
	v_mul_f32_e32 v230, 0x3fb8aa3b, v230
	v_mul_f32_e32 v231, 0x3fb8aa3b, v231
	v_mul_f32_e32 v232, 0x3fb8aa3b, v232
	v_mul_f32_e32 v233, 0x3fb8aa3b, v233
	v_mul_f32_e32 v234, 0x3fb8aa3b, v234
	v_mul_f32_e32 v235, 0x3fb8aa3b, v235
	v_exp_f32_e32 v228, v228
	v_exp_f32_e32 v229, v229
	v_exp_f32_e32 v230, v230
	v_exp_f32_e32 v231, v231
	v_exp_f32_e32 v232, v232
	v_exp_f32_e32 v233, v233
	v_exp_f32_e32 v234, v234
	v_exp_f32_e32 v235, v235
	v_add_f32_e32 v228, 1.0, v228
	v_add_f32_e32 v229, 1.0, v229
	v_add_f32_e32 v230, 1.0, v230
	v_add_f32_e32 v231, 1.0, v231
	v_add_f32_e32 v232, 1.0, v232
	v_add_f32_e32 v233, 1.0, v233
	v_add_f32_e32 v234, 1.0, v234
	v_add_f32_e32 v235, 1.0, v235
	v_rcp_f32_e32 v228, v228
	v_rcp_f32_e32 v229, v229
	v_rcp_f32_e32 v230, v230
	v_rcp_f32_e32 v231, v231
	v_rcp_f32_e32 v232, v232
	v_rcp_f32_e32 v233, v233
	v_rcp_f32_e32 v234, v234
	v_rcp_f32_e32 v235, v235
	v_pk_mul_f32 v[54:55], v[54:55], v[228:229]
	v_pk_mul_f32 v[50:51], v[50:51], v[230:231]
	v_pk_mul_f32 v[56:57], v[56:57], v[232:233]
	v_pk_mul_f32 v[52:53], v[52:53], v[234:235]
	v_cvt_pk_bf16_f32 v236, v54, v55
	v_cvt_pk_bf16_f32 v237, v56, v57
	v_cvt_pk_bf16_f32 v238, v50, v51
	v_cvt_pk_bf16_f32 v239, v52, v53
	global_store_dwordx4 v[246:247], v[236:239], off
	v_add_co_u32_e32 v152, vcc, 0x40000, v152
	s_nop 1
	v_addc_co_u32_e32 v153, vcc, 0, v153, vcc
	v_add_co_u32_e32 v246, vcc, 0x40000, v246
	s_nop 1
	v_addc_co_u32_e32 v247, vcc, 0, v247, vcc
	global_load_dwordx4 v[204:207], v[244:245], off offset:512
	global_load_dwordx4 v[208:211], v[244:245], off offset:528
	v_add_co_u32_e32 v244, vcc, 0x4000, v244
	s_nop 1
	v_addc_co_u32_e32 v245, vcc, 0, v245, vcc
	s_waitcnt vmcnt(9)
	v_pk_add_f32 v[48:49], v[48:49], v[214:215]
	v_pk_add_f32 v[46:47], v[46:47], v[212:213]
	v_pk_add_f32 v[44:45], v[44:45], v[218:219]
	v_pk_add_f32 v[42:43], v[42:43], v[216:217]
	v_mul_f32_e32 v228, 0x3d372713, v46
	v_mul_f32_e32 v229, 0x3d372713, v47
	v_mul_f32_e32 v230, 0x3d372713, v42
	v_mul_f32_e32 v231, 0x3d372713, v43
	v_mul_f32_e32 v232, 0x3d372713, v48
	v_mul_f32_e32 v233, 0x3d372713, v49
	v_mul_f32_e32 v234, 0x3d372713, v44
	v_mul_f32_e32 v235, 0x3d372713, v45
	v_mul_f32_e32 v228, v46, v228
	v_mul_f32_e32 v229, v47, v229
	v_mul_f32_e32 v230, v42, v230
	v_mul_f32_e32 v231, v43, v231
	v_mul_f32_e32 v232, v48, v232
	v_mul_f32_e32 v233, v49, v233
	v_mul_f32_e32 v234, v44, v234
	v_mul_f32_e32 v235, v45, v235
	v_fma_f32 v228, v46, v228, v46
	v_fma_f32 v229, v47, v229, v47
	v_fma_f32 v230, v42, v230, v42
	v_fma_f32 v231, v43, v231, v43
	v_fma_f32 v232, v48, v232, v48
	v_fma_f32 v233, v49, v233, v49
	v_fma_f32 v234, v44, v234, v44
	v_fma_f32 v235, v45, v235, v45
	v_mul_f32_e32 v228, 0xbfcc422a, v228
	v_mul_f32_e32 v229, 0xbfcc422a, v229
	v_mul_f32_e32 v230, 0xbfcc422a, v230
	v_mul_f32_e32 v231, 0xbfcc422a, v231
	v_mul_f32_e32 v232, 0xbfcc422a, v232
	v_mul_f32_e32 v233, 0xbfcc422a, v233
	v_mul_f32_e32 v234, 0xbfcc422a, v234
	v_mul_f32_e32 v235, 0xbfcc422a, v235
	v_mul_f32_e32 v228, 0x3fb8aa3b, v228
	v_mul_f32_e32 v229, 0x3fb8aa3b, v229
	v_mul_f32_e32 v230, 0x3fb8aa3b, v230
	v_mul_f32_e32 v231, 0x3fb8aa3b, v231
	v_mul_f32_e32 v232, 0x3fb8aa3b, v232
	v_mul_f32_e32 v233, 0x3fb8aa3b, v233
	v_mul_f32_e32 v234, 0x3fb8aa3b, v234
	v_mul_f32_e32 v235, 0x3fb8aa3b, v235
	v_exp_f32_e32 v228, v228
	v_exp_f32_e32 v229, v229
	v_exp_f32_e32 v230, v230
	v_exp_f32_e32 v231, v231
	v_exp_f32_e32 v232, v232
	v_exp_f32_e32 v233, v233
	v_exp_f32_e32 v234, v234
	v_exp_f32_e32 v235, v235
	v_add_f32_e32 v228, 1.0, v228
	v_add_f32_e32 v229, 1.0, v229
	v_add_f32_e32 v230, 1.0, v230
	v_add_f32_e32 v231, 1.0, v231
	v_add_f32_e32 v232, 1.0, v232
	v_add_f32_e32 v233, 1.0, v233
	v_add_f32_e32 v234, 1.0, v234
	v_add_f32_e32 v235, 1.0, v235
	v_rcp_f32_e32 v228, v228
	v_rcp_f32_e32 v229, v229
	v_rcp_f32_e32 v230, v230
	v_rcp_f32_e32 v231, v231
	v_rcp_f32_e32 v232, v232
	v_rcp_f32_e32 v233, v233
	v_rcp_f32_e32 v234, v234
	v_rcp_f32_e32 v235, v235
	v_pk_mul_f32 v[46:47], v[46:47], v[228:229]
	v_pk_mul_f32 v[42:43], v[42:43], v[230:231]
	v_pk_mul_f32 v[48:49], v[48:49], v[232:233]
	v_pk_mul_f32 v[44:45], v[44:45], v[234:235]
	v_cvt_pk_bf16_f32 v236, v46, v47
	v_cvt_pk_bf16_f32 v237, v48, v49
	v_cvt_pk_bf16_f32 v238, v42, v43
	v_cvt_pk_bf16_f32 v239, v44, v45
	global_store_dwordx4 v[152:153], v[236:239], off
	global_load_dwordx4 v[212:215], v[244:245], off
	global_load_dwordx4 v[216:219], v[244:245], off offset:16
	s_waitcnt vmcnt(9)
	v_pk_add_f32 v[40:41], v[40:41], v[222:223]
	v_pk_add_f32 v[38:39], v[38:39], v[220:221]
	v_pk_add_f32 v[36:37], v[36:37], v[226:227]
	v_pk_add_f32 v[34:35], v[34:35], v[224:225]
	v_mul_f32_e32 v228, 0x3d372713, v38
	v_mul_f32_e32 v229, 0x3d372713, v39
	v_mul_f32_e32 v230, 0x3d372713, v34
	v_mul_f32_e32 v231, 0x3d372713, v35
	v_mul_f32_e32 v232, 0x3d372713, v40
	v_mul_f32_e32 v233, 0x3d372713, v41
	v_mul_f32_e32 v234, 0x3d372713, v36
	v_mul_f32_e32 v235, 0x3d372713, v37
	v_mul_f32_e32 v228, v38, v228
	v_mul_f32_e32 v229, v39, v229
	v_mul_f32_e32 v230, v34, v230
	v_mul_f32_e32 v231, v35, v231
	v_mul_f32_e32 v232, v40, v232
	v_mul_f32_e32 v233, v41, v233
	v_mul_f32_e32 v234, v36, v234
	v_mul_f32_e32 v235, v37, v235
	v_fma_f32 v228, v38, v228, v38
	v_fma_f32 v229, v39, v229, v39
	v_fma_f32 v230, v34, v230, v34
	v_fma_f32 v231, v35, v231, v35
	v_fma_f32 v232, v40, v232, v40
	v_fma_f32 v233, v41, v233, v41
	v_fma_f32 v234, v36, v234, v36
	v_fma_f32 v235, v37, v235, v37
	v_mul_f32_e32 v228, 0xbfcc422a, v228
	v_mul_f32_e32 v229, 0xbfcc422a, v229
	v_mul_f32_e32 v230, 0xbfcc422a, v230
	v_mul_f32_e32 v231, 0xbfcc422a, v231
	v_mul_f32_e32 v232, 0xbfcc422a, v232
	v_mul_f32_e32 v233, 0xbfcc422a, v233
	v_mul_f32_e32 v234, 0xbfcc422a, v234
	v_mul_f32_e32 v235, 0xbfcc422a, v235
	v_mul_f32_e32 v228, 0x3fb8aa3b, v228
	v_mul_f32_e32 v229, 0x3fb8aa3b, v229
	v_mul_f32_e32 v230, 0x3fb8aa3b, v230
	v_mul_f32_e32 v231, 0x3fb8aa3b, v231
	v_mul_f32_e32 v232, 0x3fb8aa3b, v232
	v_mul_f32_e32 v233, 0x3fb8aa3b, v233
	v_mul_f32_e32 v234, 0x3fb8aa3b, v234
	v_mul_f32_e32 v235, 0x3fb8aa3b, v235
	v_exp_f32_e32 v228, v228
	v_exp_f32_e32 v229, v229
	v_exp_f32_e32 v230, v230
	v_exp_f32_e32 v231, v231
	v_exp_f32_e32 v232, v232
	v_exp_f32_e32 v233, v233
	v_exp_f32_e32 v234, v234
	v_exp_f32_e32 v235, v235
	v_add_f32_e32 v228, 1.0, v228
	v_add_f32_e32 v229, 1.0, v229
	v_add_f32_e32 v230, 1.0, v230
	v_add_f32_e32 v231, 1.0, v231
	v_add_f32_e32 v232, 1.0, v232
	v_add_f32_e32 v233, 1.0, v233
	v_add_f32_e32 v234, 1.0, v234
	v_add_f32_e32 v235, 1.0, v235
	v_rcp_f32_e32 v228, v228
	v_rcp_f32_e32 v229, v229
	v_rcp_f32_e32 v230, v230
	v_rcp_f32_e32 v231, v231
	v_rcp_f32_e32 v232, v232
	v_rcp_f32_e32 v233, v233
	v_rcp_f32_e32 v234, v234
	v_rcp_f32_e32 v235, v235
	v_pk_mul_f32 v[38:39], v[38:39], v[228:229]
	v_pk_mul_f32 v[34:35], v[34:35], v[230:231]
	v_pk_mul_f32 v[40:41], v[40:41], v[232:233]
	v_pk_mul_f32 v[36:37], v[36:37], v[234:235]
	v_cvt_pk_bf16_f32 v236, v38, v39
	v_cvt_pk_bf16_f32 v237, v40, v41
	v_cvt_pk_bf16_f32 v238, v34, v35
	v_cvt_pk_bf16_f32 v239, v36, v37
	global_store_dwordx4 v[246:247], v[236:239], off
	v_add_co_u32_e32 v152, vcc, 0x40000, v152
	s_nop 1
	v_addc_co_u32_e32 v153, vcc, 0, v153, vcc
	v_add_co_u32_e32 v246, vcc, 0x40000, v246
	s_nop 1
	v_addc_co_u32_e32 v247, vcc, 0, v247, vcc
	global_load_dwordx4 v[220:223], v[244:245], off offset:512
	global_load_dwordx4 v[224:227], v[244:245], off offset:528
	s_waitcnt vmcnt(9)
	v_pk_add_f32 v[32:33], v[32:33], v[198:199]
	v_pk_add_f32 v[30:31], v[30:31], v[196:197]
	v_pk_add_f32 v[28:29], v[28:29], v[202:203]
	v_pk_add_f32 v[26:27], v[26:27], v[200:201]
	v_mul_f32_e32 v228, 0x3d372713, v30
	v_mul_f32_e32 v229, 0x3d372713, v31
	v_mul_f32_e32 v230, 0x3d372713, v26
	v_mul_f32_e32 v231, 0x3d372713, v27
	v_mul_f32_e32 v232, 0x3d372713, v32
	v_mul_f32_e32 v233, 0x3d372713, v33
	v_mul_f32_e32 v234, 0x3d372713, v28
	v_mul_f32_e32 v235, 0x3d372713, v29
	v_mul_f32_e32 v228, v30, v228
	v_mul_f32_e32 v229, v31, v229
	v_mul_f32_e32 v230, v26, v230
	v_mul_f32_e32 v231, v27, v231
	v_mul_f32_e32 v232, v32, v232
	v_mul_f32_e32 v233, v33, v233
	v_mul_f32_e32 v234, v28, v234
	v_mul_f32_e32 v235, v29, v235
	v_fma_f32 v228, v30, v228, v30
	v_fma_f32 v229, v31, v229, v31
	v_fma_f32 v230, v26, v230, v26
	v_fma_f32 v231, v27, v231, v27
	v_fma_f32 v232, v32, v232, v32
	v_fma_f32 v233, v33, v233, v33
	v_fma_f32 v234, v28, v234, v28
	v_fma_f32 v235, v29, v235, v29
	v_mul_f32_e32 v228, 0xbfcc422a, v228
	v_mul_f32_e32 v229, 0xbfcc422a, v229
	v_mul_f32_e32 v230, 0xbfcc422a, v230
	v_mul_f32_e32 v231, 0xbfcc422a, v231
	v_mul_f32_e32 v232, 0xbfcc422a, v232
	v_mul_f32_e32 v233, 0xbfcc422a, v233
	v_mul_f32_e32 v234, 0xbfcc422a, v234
	v_mul_f32_e32 v235, 0xbfcc422a, v235
	v_mul_f32_e32 v228, 0x3fb8aa3b, v228
	v_mul_f32_e32 v229, 0x3fb8aa3b, v229
	v_mul_f32_e32 v230, 0x3fb8aa3b, v230
	v_mul_f32_e32 v231, 0x3fb8aa3b, v231
	v_mul_f32_e32 v232, 0x3fb8aa3b, v232
	v_mul_f32_e32 v233, 0x3fb8aa3b, v233
	v_mul_f32_e32 v234, 0x3fb8aa3b, v234
	v_mul_f32_e32 v235, 0x3fb8aa3b, v235
	v_exp_f32_e32 v228, v228
	v_exp_f32_e32 v229, v229
	v_exp_f32_e32 v230, v230
	v_exp_f32_e32 v231, v231
	v_exp_f32_e32 v232, v232
	v_exp_f32_e32 v233, v233
	v_exp_f32_e32 v234, v234
	v_exp_f32_e32 v235, v235
	v_add_f32_e32 v228, 1.0, v228
	v_add_f32_e32 v229, 1.0, v229
	v_add_f32_e32 v230, 1.0, v230
	v_add_f32_e32 v231, 1.0, v231
	v_add_f32_e32 v232, 1.0, v232
	v_add_f32_e32 v233, 1.0, v233
	v_add_f32_e32 v234, 1.0, v234
	v_add_f32_e32 v235, 1.0, v235
	v_rcp_f32_e32 v228, v228
	v_rcp_f32_e32 v229, v229
	v_rcp_f32_e32 v230, v230
	v_rcp_f32_e32 v231, v231
	v_rcp_f32_e32 v232, v232
	v_rcp_f32_e32 v233, v233
	v_rcp_f32_e32 v234, v234
	v_rcp_f32_e32 v235, v235
	v_pk_mul_f32 v[30:31], v[30:31], v[228:229]
	v_pk_mul_f32 v[26:27], v[26:27], v[230:231]
	v_pk_mul_f32 v[32:33], v[32:33], v[232:233]
	v_pk_mul_f32 v[28:29], v[28:29], v[234:235]
	v_cvt_pk_bf16_f32 v236, v30, v31
	v_cvt_pk_bf16_f32 v237, v32, v33
	v_cvt_pk_bf16_f32 v238, v26, v27
	v_cvt_pk_bf16_f32 v239, v28, v29
	global_store_dwordx4 v[152:153], v[236:239], off
	s_waitcnt vmcnt(7)
	v_pk_add_f32 v[24:25], v[24:25], v[206:207]
	v_pk_add_f32 v[22:23], v[22:23], v[204:205]
	v_pk_add_f32 v[20:21], v[20:21], v[210:211]
	v_pk_add_f32 v[18:19], v[18:19], v[208:209]
	v_mul_f32_e32 v228, 0x3d372713, v22
	v_mul_f32_e32 v229, 0x3d372713, v23
	v_mul_f32_e32 v230, 0x3d372713, v18
	v_mul_f32_e32 v231, 0x3d372713, v19
	v_mul_f32_e32 v232, 0x3d372713, v24
	v_mul_f32_e32 v233, 0x3d372713, v25
	v_mul_f32_e32 v234, 0x3d372713, v20
	v_mul_f32_e32 v235, 0x3d372713, v21
	v_mul_f32_e32 v228, v22, v228
	v_mul_f32_e32 v229, v23, v229
	v_mul_f32_e32 v230, v18, v230
	v_mul_f32_e32 v231, v19, v231
	v_mul_f32_e32 v232, v24, v232
	v_mul_f32_e32 v233, v25, v233
	v_mul_f32_e32 v234, v20, v234
	v_mul_f32_e32 v235, v21, v235
	v_fma_f32 v228, v22, v228, v22
	v_fma_f32 v229, v23, v229, v23
	v_fma_f32 v230, v18, v230, v18
	v_fma_f32 v231, v19, v231, v19
	v_fma_f32 v232, v24, v232, v24
	v_fma_f32 v233, v25, v233, v25
	v_fma_f32 v234, v20, v234, v20
	v_fma_f32 v235, v21, v235, v21
	v_mul_f32_e32 v228, 0xbfcc422a, v228
	v_mul_f32_e32 v229, 0xbfcc422a, v229
	v_mul_f32_e32 v230, 0xbfcc422a, v230
	v_mul_f32_e32 v231, 0xbfcc422a, v231
	v_mul_f32_e32 v232, 0xbfcc422a, v232
	v_mul_f32_e32 v233, 0xbfcc422a, v233
	v_mul_f32_e32 v234, 0xbfcc422a, v234
	v_mul_f32_e32 v235, 0xbfcc422a, v235
	v_mul_f32_e32 v228, 0x3fb8aa3b, v228
	v_mul_f32_e32 v229, 0x3fb8aa3b, v229
	v_mul_f32_e32 v230, 0x3fb8aa3b, v230
	v_mul_f32_e32 v231, 0x3fb8aa3b, v231
	v_mul_f32_e32 v232, 0x3fb8aa3b, v232
	v_mul_f32_e32 v233, 0x3fb8aa3b, v233
	v_mul_f32_e32 v234, 0x3fb8aa3b, v234
	v_mul_f32_e32 v235, 0x3fb8aa3b, v235
	v_exp_f32_e32 v228, v228
	v_exp_f32_e32 v229, v229
	v_exp_f32_e32 v230, v230
	v_exp_f32_e32 v231, v231
	v_exp_f32_e32 v232, v232
	v_exp_f32_e32 v233, v233
	v_exp_f32_e32 v234, v234
	v_exp_f32_e32 v235, v235
	v_add_f32_e32 v228, 1.0, v228
	v_add_f32_e32 v229, 1.0, v229
	v_add_f32_e32 v230, 1.0, v230
	v_add_f32_e32 v231, 1.0, v231
	v_add_f32_e32 v232, 1.0, v232
	v_add_f32_e32 v233, 1.0, v233
	v_add_f32_e32 v234, 1.0, v234
	v_add_f32_e32 v235, 1.0, v235
	v_rcp_f32_e32 v228, v228
	v_rcp_f32_e32 v229, v229
	v_rcp_f32_e32 v230, v230
	v_rcp_f32_e32 v231, v231
	v_rcp_f32_e32 v232, v232
	v_rcp_f32_e32 v233, v233
	v_rcp_f32_e32 v234, v234
	v_rcp_f32_e32 v235, v235
	v_pk_mul_f32 v[22:23], v[22:23], v[228:229]
	v_pk_mul_f32 v[18:19], v[18:19], v[230:231]
	v_pk_mul_f32 v[24:25], v[24:25], v[232:233]
	v_pk_mul_f32 v[20:21], v[20:21], v[234:235]
	v_cvt_pk_bf16_f32 v236, v22, v23
	v_cvt_pk_bf16_f32 v237, v24, v25
	v_cvt_pk_bf16_f32 v238, v18, v19
	v_cvt_pk_bf16_f32 v239, v20, v21
	global_store_dwordx4 v[246:247], v[236:239], off
	v_add_co_u32_e32 v152, vcc, 0x40000, v152
	s_nop 1
	v_addc_co_u32_e32 v153, vcc, 0, v153, vcc
	v_add_co_u32_e32 v246, vcc, 0x40000, v246
	s_nop 1
	v_addc_co_u32_e32 v247, vcc, 0, v247, vcc
	s_waitcnt vmcnt(5)
	v_pk_add_f32 v[16:17], v[16:17], v[214:215]
	v_pk_add_f32 v[14:15], v[14:15], v[212:213]
	v_pk_add_f32 v[12:13], v[12:13], v[218:219]
	v_pk_add_f32 v[10:11], v[10:11], v[216:217]
	v_mul_f32_e32 v228, 0x3d372713, v14
	v_mul_f32_e32 v229, 0x3d372713, v15
	v_mul_f32_e32 v230, 0x3d372713, v10
	v_mul_f32_e32 v231, 0x3d372713, v11
	v_mul_f32_e32 v232, 0x3d372713, v16
	v_mul_f32_e32 v233, 0x3d372713, v17
	v_mul_f32_e32 v234, 0x3d372713, v12
	v_mul_f32_e32 v235, 0x3d372713, v13
	v_mul_f32_e32 v228, v14, v228
	v_mul_f32_e32 v229, v15, v229
	v_mul_f32_e32 v230, v10, v230
	v_mul_f32_e32 v231, v11, v231
	v_mul_f32_e32 v232, v16, v232
	v_mul_f32_e32 v233, v17, v233
	v_mul_f32_e32 v234, v12, v234
	v_mul_f32_e32 v235, v13, v235
	v_fma_f32 v228, v14, v228, v14
	v_fma_f32 v229, v15, v229, v15
	v_fma_f32 v230, v10, v230, v10
	v_fma_f32 v231, v11, v231, v11
	v_fma_f32 v232, v16, v232, v16
	v_fma_f32 v233, v17, v233, v17
	v_fma_f32 v234, v12, v234, v12
	v_fma_f32 v235, v13, v235, v13
	v_mul_f32_e32 v228, 0xbfcc422a, v228
	v_mul_f32_e32 v229, 0xbfcc422a, v229
	v_mul_f32_e32 v230, 0xbfcc422a, v230
	v_mul_f32_e32 v231, 0xbfcc422a, v231
	v_mul_f32_e32 v232, 0xbfcc422a, v232
	v_mul_f32_e32 v233, 0xbfcc422a, v233
	v_mul_f32_e32 v234, 0xbfcc422a, v234
	v_mul_f32_e32 v235, 0xbfcc422a, v235
	v_mul_f32_e32 v228, 0x3fb8aa3b, v228
	v_mul_f32_e32 v229, 0x3fb8aa3b, v229
	v_mul_f32_e32 v230, 0x3fb8aa3b, v230
	v_mul_f32_e32 v231, 0x3fb8aa3b, v231
	v_mul_f32_e32 v232, 0x3fb8aa3b, v232
	v_mul_f32_e32 v233, 0x3fb8aa3b, v233
	v_mul_f32_e32 v234, 0x3fb8aa3b, v234
	v_mul_f32_e32 v235, 0x3fb8aa3b, v235
	v_exp_f32_e32 v228, v228
	v_exp_f32_e32 v229, v229
	v_exp_f32_e32 v230, v230
	v_exp_f32_e32 v231, v231
	v_exp_f32_e32 v232, v232
	v_exp_f32_e32 v233, v233
	v_exp_f32_e32 v234, v234
	v_exp_f32_e32 v235, v235
	v_add_f32_e32 v228, 1.0, v228
	v_add_f32_e32 v229, 1.0, v229
	v_add_f32_e32 v230, 1.0, v230
	v_add_f32_e32 v231, 1.0, v231
	v_add_f32_e32 v232, 1.0, v232
	v_add_f32_e32 v233, 1.0, v233
	v_add_f32_e32 v234, 1.0, v234
	v_add_f32_e32 v235, 1.0, v235
	v_rcp_f32_e32 v228, v228
	v_rcp_f32_e32 v229, v229
	v_rcp_f32_e32 v230, v230
	v_rcp_f32_e32 v231, v231
	v_rcp_f32_e32 v232, v232
	v_rcp_f32_e32 v233, v233
	v_rcp_f32_e32 v234, v234
	v_rcp_f32_e32 v235, v235
	v_pk_mul_f32 v[14:15], v[14:15], v[228:229]
	v_pk_mul_f32 v[10:11], v[10:11], v[230:231]
	v_pk_mul_f32 v[16:17], v[16:17], v[232:233]
	v_pk_mul_f32 v[12:13], v[12:13], v[234:235]
	v_cvt_pk_bf16_f32 v236, v14, v15
	v_cvt_pk_bf16_f32 v237, v16, v17
	v_cvt_pk_bf16_f32 v238, v10, v11
	v_cvt_pk_bf16_f32 v239, v12, v13
	global_store_dwordx4 v[152:153], v[236:239], off
	s_waitcnt vmcnt(3)
	v_pk_add_f32 v[8:9], v[8:9], v[222:223]
	v_pk_add_f32 v[6:7], v[6:7], v[220:221]
	v_pk_add_f32 v[4:5], v[4:5], v[226:227]
	v_pk_add_f32 v[2:3], v[2:3], v[224:225]
	v_mul_f32_e32 v228, 0x3d372713, v6
	v_mul_f32_e32 v229, 0x3d372713, v7
	v_mul_f32_e32 v230, 0x3d372713, v2
	v_mul_f32_e32 v231, 0x3d372713, v3
	v_mul_f32_e32 v232, 0x3d372713, v8
	v_mul_f32_e32 v233, 0x3d372713, v9
	v_mul_f32_e32 v234, 0x3d372713, v4
	v_mul_f32_e32 v235, 0x3d372713, v5
	v_mul_f32_e32 v228, v6, v228
	v_mul_f32_e32 v229, v7, v229
	v_mul_f32_e32 v230, v2, v230
	v_mul_f32_e32 v231, v3, v231
	v_mul_f32_e32 v232, v8, v232
	v_mul_f32_e32 v233, v9, v233
	v_mul_f32_e32 v234, v4, v234
	v_mul_f32_e32 v235, v5, v235
	v_fma_f32 v228, v6, v228, v6
	v_fma_f32 v229, v7, v229, v7
	v_fma_f32 v230, v2, v230, v2
	v_fma_f32 v231, v3, v231, v3
	v_fma_f32 v232, v8, v232, v8
	v_fma_f32 v233, v9, v233, v9
	v_fma_f32 v234, v4, v234, v4
	v_fma_f32 v235, v5, v235, v5
	v_mul_f32_e32 v228, 0xbfcc422a, v228
	v_mul_f32_e32 v229, 0xbfcc422a, v229
	v_mul_f32_e32 v230, 0xbfcc422a, v230
	v_mul_f32_e32 v231, 0xbfcc422a, v231
	v_mul_f32_e32 v232, 0xbfcc422a, v232
	v_mul_f32_e32 v233, 0xbfcc422a, v233
	v_mul_f32_e32 v234, 0xbfcc422a, v234
	v_mul_f32_e32 v235, 0xbfcc422a, v235
	v_mul_f32_e32 v228, 0x3fb8aa3b, v228
	v_mul_f32_e32 v229, 0x3fb8aa3b, v229
	v_mul_f32_e32 v230, 0x3fb8aa3b, v230
	v_mul_f32_e32 v231, 0x3fb8aa3b, v231
	v_mul_f32_e32 v232, 0x3fb8aa3b, v232
	v_mul_f32_e32 v233, 0x3fb8aa3b, v233
	v_mul_f32_e32 v234, 0x3fb8aa3b, v234
	v_mul_f32_e32 v235, 0x3fb8aa3b, v235
	v_exp_f32_e32 v228, v228
	v_exp_f32_e32 v229, v229
	v_exp_f32_e32 v230, v230
	v_exp_f32_e32 v231, v231
	v_exp_f32_e32 v232, v232
	v_exp_f32_e32 v233, v233
	v_exp_f32_e32 v234, v234
	v_exp_f32_e32 v235, v235
	v_add_f32_e32 v228, 1.0, v228
	v_add_f32_e32 v229, 1.0, v229
	v_add_f32_e32 v230, 1.0, v230
	v_add_f32_e32 v231, 1.0, v231
	v_add_f32_e32 v232, 1.0, v232
	v_add_f32_e32 v233, 1.0, v233
	v_add_f32_e32 v234, 1.0, v234
	v_add_f32_e32 v235, 1.0, v235
	v_rcp_f32_e32 v228, v228
	v_rcp_f32_e32 v229, v229
	v_rcp_f32_e32 v230, v230
	v_rcp_f32_e32 v231, v231
	v_rcp_f32_e32 v232, v232
	v_rcp_f32_e32 v233, v233
	v_rcp_f32_e32 v234, v234
	v_rcp_f32_e32 v235, v235
	v_pk_mul_f32 v[6:7], v[6:7], v[228:229]
	v_pk_mul_f32 v[2:3], v[2:3], v[230:231]
	v_pk_mul_f32 v[8:9], v[8:9], v[232:233]
	v_pk_mul_f32 v[4:5], v[4:5], v[234:235]
	v_cvt_pk_bf16_f32 v236, v6, v7
	v_cvt_pk_bf16_f32 v237, v8, v9
	v_cvt_pk_bf16_f32 v238, v2, v3
	v_cvt_pk_bf16_f32 v239, v4, v5
	global_store_dwordx4 v[246:247], v[236:239], off
	s_waitcnt vmcnt(0)
	s_barrier

.LBB0_1492:
	v_mov_b32_e32 v44, v173
	v_and_b32_e32 v30, 64, v189
	v_ashrrev_i32_e32 v45, 2, v44
	v_add_u32_e32 v0, s6, v45
	v_mad_i64_i32 v[2:3], s[2:3], v0, s84, 0
	v_and_b32_e32 v0, 3, v44
	s_add_u32 s2, s14, s0
	v_lshl_or_b32 v2, v0, 5, v2
	s_addc_u32 s3, s15, s1
	v_lshl_add_u64 v[6:7], s[2:3], 0, v[2:3]
	s_mov_b64 s[2:3], 0xd700400
	v_lshl_add_u64 v[2:3], v[6:7], 0, s[2:3]
	v_add_co_u32_e32 v6, vcc, s75, v6
	global_load_dwordx4 v[2:5], v[2:3], off offset:16
	s_nop 0
	v_addc_co_u32_e32 v7, vcc, 0, v7, vcc
	global_load_dwordx4 v[6:9], v[6:7], off offset:1024
	v_add_u32_e32 v46, 64, v30
	v_xor_b32_e32 v0, 1, v189
	v_cmp_lt_i32_e32 vcc, v0, v46
	s_add_u32 s2, s7, s0
	s_addc_u32 s3, 0, s1
	v_cndmask_b32_e32 v0, v189, v0, vcc
	v_lshlrev_b32_e32 v47, 2, v0
	s_waitcnt vmcnt(1)
	v_and_b32_e32 v10, 0xffff0000, v2
	v_lshlrev_b32_e32 v11, 16, v2
	v_mul_f32_e32 v14, 0x3d372713, v11
	s_waitcnt vmcnt(0)
	v_lshlrev_b32_e32 v30, 16, v6
	v_and_b32_e32 v31, 0xffff0000, v6
	v_mul_f32_e32 v6, 0x3d372713, v30
	v_mul_f32_e32 v6, v6, v30
	v_mov_b32_e32 v32, v30
	v_fmac_f32_e32 v32, v6, v32
	v_mul_f32_e32 v6, 0xbfcc422a, v32
	v_mul_f32_e32 v32, 0x3d372713, v31
	v_mul_f32_e32 v32, v32, v31
	v_mov_b32_e32 v33, v31
	v_fmac_f32_e32 v33, v32, v33
	v_mul_f32_e32 v6, 0x3fb8aa3b, v6
	v_mul_f32_e32 v32, 0xbfcc422a, v33
	v_exp_f32_e32 v6, v6
	v_mul_f32_e32 v32, 0x3fb8aa3b, v32
	v_exp_f32_e32 v32, v32
	v_and_b32_e32 v33, 0xffff0000, v7
	v_add_f32_e32 v0, 1.0, v6
	v_rcp_f32_e32 v6, v0
	v_add_f32_e32 v0, 1.0, v32
	v_lshlrev_b32_e32 v32, 16, v7
	v_mul_f32_e32 v7, 0x3d372713, v32
	v_mul_f32_e32 v7, v7, v32
	v_mov_b32_e32 v34, v32
	v_fmac_f32_e32 v34, v7, v34
	v_mul_f32_e32 v7, 0xbfcc422a, v34
	v_mul_f32_e32 v7, 0x3fb8aa3b, v7
	v_exp_f32_e32 v34, v7
	v_mul_f32_e32 v7, 0x3d372713, v33
	v_mul_f32_e32 v7, v7, v33
	v_mov_b32_e32 v35, v33
	v_fmac_f32_e32 v35, v7, v35
	v_mul_f32_e32 v7, 0xbfcc422a, v35
	v_mul_f32_e32 v7, 0x3fb8aa3b, v7
	v_exp_f32_e32 v35, v7
	v_rcp_f32_e32 v7, v0
	v_add_f32_e32 v0, 1.0, v34
	v_rcp_f32_e32 v34, v0
	v_add_f32_e32 v0, 1.0, v35
	v_rcp_f32_e32 v35, v0
	v_pk_mul_f32 v[36:37], v[6:7], v[30:31]
	v_lshlrev_b32_e32 v38, 16, v8
	v_add_f32_e32 v0, 0, v36
	v_add_f32_e32 v0, v37, v0
	v_pk_mul_f32 v[36:37], v[34:35], v[32:33]
	v_and_b32_e32 v39, 0xffff0000, v8
	v_mul_f32_e32 v8, 0x3d372713, v38
	v_add_f32_e32 v0, v36, v0
	v_mul_f32_e32 v8, v8, v38
	v_mov_b32_e32 v36, v38
	v_fmac_f32_e32 v36, v8, v36
	v_mul_f32_e32 v8, 0xbfcc422a, v36
	v_mul_f32_e32 v36, 0x3d372713, v39
	v_mul_f32_e32 v36, v36, v39
	v_mov_b32_e32 v40, v39
	v_fmac_f32_e32 v40, v36, v40
	v_mul_f32_e32 v36, 0xbfcc422a, v40
	v_mul_f32_e32 v36, 0x3fb8aa3b, v36
	v_exp_f32_e32 v36, v36
	v_add_f32_e32 v0, v37, v0
	v_and_b32_e32 v37, 0xffff0000, v9
	v_mov_b32_e32 v42, v37
	v_add_f32_e32 v40, 1.0, v36
	v_lshlrev_b32_e32 v36, 16, v9
	v_mul_f32_e32 v9, 0x3d372713, v36
	v_mul_f32_e32 v9, v9, v36
	v_mov_b32_e32 v41, v36
	v_fmac_f32_e32 v41, v9, v41
	v_mul_f32_e32 v9, 0xbfcc422a, v41
	v_mul_f32_e32 v9, 0x3fb8aa3b, v9
	v_exp_f32_e32 v41, v9
	v_mul_f32_e32 v9, 0x3d372713, v37
	v_mul_f32_e32 v9, v9, v37
	v_mul_f32_e32 v16, 0x3d372713, v10
	v_mul_f32_e32 v8, 0x3fb8aa3b, v8
	v_fmac_f32_e32 v42, v9, v42
	v_and_b32_e32 v2, 0xffff0000, v3
	v_lshlrev_b32_e32 v3, 16, v3
	v_mov_b32_e32 v15, v11
	v_mov_b32_e32 v17, v10
	v_mul_f32_e32 v14, v14, v11
	v_mul_f32_e32 v16, v16, v10
	v_exp_f32_e32 v8, v8
	v_mul_f32_e32 v9, 0xbfcc422a, v42
	v_mul_f32_e32 v18, 0x3d372713, v3
	v_mul_f32_e32 v20, 0x3d372713, v2
	v_fmac_f32_e32 v15, v14, v15
	v_fmac_f32_e32 v17, v16, v17
	v_mul_f32_e32 v9, 0x3fb8aa3b, v9
	v_and_b32_e32 v12, 0xffff0000, v4
	v_lshlrev_b32_e32 v13, 16, v4
	v_mov_b32_e32 v19, v3
	v_mov_b32_e32 v21, v2
	v_mul_f32_e32 v18, v18, v3
	v_mul_f32_e32 v20, v20, v2
	v_mul_f32_e32 v14, 0xbfcc422a, v15
	v_mul_f32_e32 v15, 0xbfcc422a, v17
	v_exp_f32_e32 v42, v9
	v_mul_f32_e32 v22, 0x3d372713, v13
	v_mul_f32_e32 v24, 0x3d372713, v12
	v_fmac_f32_e32 v19, v18, v19
	v_fmac_f32_e32 v21, v20, v21
	v_mul_f32_e32 v14, 0x3fb8aa3b, v14
	v_mul_f32_e32 v15, 0x3fb8aa3b, v15
	v_and_b32_e32 v4, 0xffff0000, v5
	v_lshlrev_b32_e32 v5, 16, v5
	v_mov_b32_e32 v23, v13
	v_mov_b32_e32 v25, v12
	v_mul_f32_e32 v22, v22, v13
	v_mul_f32_e32 v24, v24, v12
	v_mul_f32_e32 v16, 0xbfcc422a, v19
	v_mul_f32_e32 v17, 0xbfcc422a, v21
	v_exp_f32_e32 v14, v14
	v_exp_f32_e32 v15, v15
	v_add_f32_e32 v8, 1.0, v8
	v_mul_f32_e32 v26, 0x3d372713, v5
	v_mul_f32_e32 v28, 0x3d372713, v4
	v_fmac_f32_e32 v23, v22, v23
	v_fmac_f32_e32 v25, v24, v25
	v_mul_f32_e32 v16, 0x3fb8aa3b, v16
	v_mul_f32_e32 v17, 0x3fb8aa3b, v17
	v_rcp_f32_e32 v8, v8
	v_rcp_f32_e32 v9, v40
	v_mov_b32_e32 v27, v5
	v_mov_b32_e32 v29, v4
	v_mul_f32_e32 v26, v26, v5
	v_mul_f32_e32 v28, v28, v4
	v_mul_f32_e32 v18, 0xbfcc422a, v23
	v_mul_f32_e32 v19, 0xbfcc422a, v25
	v_exp_f32_e32 v16, v16
	v_exp_f32_e32 v17, v17
	v_add_f32_e32 v40, 1.0, v41
	v_add_f32_e32 v41, 1.0, v42
	v_fmac_f32_e32 v27, v26, v27
	v_fmac_f32_e32 v29, v28, v29
	v_mul_f32_e32 v18, 0x3fb8aa3b, v18
	v_mul_f32_e32 v19, 0x3fb8aa3b, v19
	v_rcp_f32_e32 v40, v40
	v_rcp_f32_e32 v41, v41
	v_mul_f32_e32 v20, 0xbfcc422a, v27
	v_mul_f32_e32 v21, 0xbfcc422a, v29
	v_exp_f32_e32 v18, v18
	v_exp_f32_e32 v19, v19
	v_add_f32_e32 v14, 1.0, v14
	v_add_f32_e32 v22, 1.0, v15
	v_mul_f32_e32 v20, 0x3fb8aa3b, v20
	v_mul_f32_e32 v21, 0x3fb8aa3b, v21
	v_rcp_f32_e32 v15, v14
	v_rcp_f32_e32 v14, v22
	v_pk_mul_f32 v[42:43], v[8:9], v[38:39]
	v_exp_f32_e32 v20, v20
	v_exp_f32_e32 v21, v21
	v_add_f32_e32 v16, 1.0, v16
	v_add_f32_e32 v23, 1.0, v17
	v_add_f32_e32 v0, v42, v0
	v_rcp_f32_e32 v17, v16
	v_rcp_f32_e32 v16, v23
	v_add_f32_e32 v0, v43, v0
	v_pk_mul_f32 v[42:43], v[40:41], v[36:37]
	v_add_f32_e32 v18, 1.0, v18
	v_add_f32_e32 v24, 1.0, v19
	v_add_f32_e32 v0, v42, v0
	v_rcp_f32_e32 v19, v18
	v_rcp_f32_e32 v18, v24
	v_pk_mul_f32 v[22:23], v[14:15], v[10:11]
	v_add_f32_e32 v0, v43, v0
	v_add_f32_e32 v20, 1.0, v20
	v_add_f32_e32 v25, 1.0, v21
	v_add_f32_e32 v0, v23, v0
	v_rcp_f32_e32 v21, v20
	v_rcp_f32_e32 v20, v25
	v_pk_mul_f32 v[24:25], v[16:17], v[2:3]
	v_add_f32_e32 v0, v22, v0
	v_add_f32_e32 v0, v25, v0
	v_pk_mul_f32 v[26:27], v[18:19], v[12:13]
	v_add_f32_e32 v0, v24, v0
	v_add_f32_e32 v0, v27, v0
	v_pk_mul_f32 v[28:29], v[20:21], v[4:5]
	v_add_f32_e32 v0, v26, v0
	v_add_f32_e32 v0, v29, v0
	v_add_f32_e32 v0, v28, v0
	ds_bpermute_b32 v22, v47, v0
	v_xor_b32_e32 v23, 2, v189
	v_cmp_lt_i32_e32 vcc, v23, v46
	s_waitcnt lgkmcnt(0)
	v_add_f32_e32 v0, v0, v22
	v_cndmask_b32_e32 v23, v189, v23, vcc
	v_lshlrev_b32_e32 v42, 2, v23
	ds_bpermute_b32 v22, v42, v0
	s_waitcnt lgkmcnt(0)
	v_add_f32_e32 v0, v0, v22
	v_mul_f32_e32 v0, 0x3c800000, v0
	v_pk_fma_f32 v[6:7], v[6:7], v[30:31], v[0:1] op_sel_hi:[1,1,0] neg_lo:[0,0,1] neg_hi:[0,0,1]
	v_pk_fma_f32 v[24:25], v[34:35], v[32:33], v[0:1] op_sel_hi:[1,1,0] neg_lo:[0,0,1] neg_hi:[0,0,1]
	v_pk_mul_f32 v[22:23], v[6:7], v[6:7]
	v_pk_mul_f32 v[26:27], v[24:25], v[24:25]
	v_pk_fma_f32 v[8:9], v[8:9], v[38:39], v[0:1] op_sel_hi:[1,1,0] neg_lo:[0,0,1] neg_hi:[0,0,1]
	v_pk_fma_f32 v[30:31], v[40:41], v[36:37], v[0:1] op_sel_hi:[1,1,0] neg_lo:[0,0,1] neg_hi:[0,0,1]
	v_pk_fma_f32 v[12:13], v[18:19], v[12:13], v[0:1] op_sel_hi:[1,1,0] neg_lo:[0,0,1] neg_hi:[0,0,1]
	v_pk_fma_f32 v[4:5], v[20:21], v[4:5], v[0:1] op_sel_hi:[1,1,0] neg_lo:[0,0,1] neg_hi:[0,0,1]
	v_pk_fma_f32 v[10:11], v[14:15], v[10:11], v[0:1] op_sel_hi:[1,1,0] neg_lo:[0,0,1] neg_hi:[0,0,1]
	v_pk_fma_f32 v[2:3], v[16:17], v[2:3], v[0:1] op_sel_hi:[1,1,0] neg_lo:[0,0,1] neg_hi:[0,0,1]
	v_add_f32_e32 v0, v22, v23
	v_add_f32_e32 v0, v26, v0
	v_pk_mul_f32 v[28:29], v[8:9], v[8:9]
	v_add_f32_e32 v0, v27, v0
	v_add_f32_e32 v0, v28, v0
	v_pk_mul_f32 v[32:33], v[30:31], v[30:31]
	v_add_f32_e32 v0, v29, v0
	v_add_f32_e32 v0, v32, v0
	v_pk_mul_f32 v[14:15], v[10:11], v[10:11]
	v_add_f32_e32 v0, v33, v0
	v_add_f32_e32 v0, v15, v0
	v_pk_mul_f32 v[16:17], v[2:3], v[2:3]
	v_add_f32_e32 v0, v14, v0
	v_add_f32_e32 v0, v17, v0
	v_pk_mul_f32 v[18:19], v[12:13], v[12:13]
	v_add_f32_e32 v0, v16, v0
	v_add_f32_e32 v0, v19, v0
	v_pk_mul_f32 v[20:21], v[4:5], v[4:5]
	v_add_f32_e32 v0, v18, v0
	v_add_f32_e32 v0, v21, v0
	v_add_f32_e32 v0, v20, v0
	ds_bpermute_b32 v14, v47, v0
	v_lshlrev_b32_e32 v15, 4, v44
	v_and_b32_e32 v15, 48, v15
	v_mul_u32_u24_e32 v15, 0x88, v15
	v_lshlrev_b32_e32 v16, 1, v45
	s_waitcnt lgkmcnt(0)
	v_add_f32_e32 v0, v0, v14
	ds_bpermute_b32 v14, v42, v0
	v_bfe_u32 v22, v44, 5, 1
	s_waitcnt lgkmcnt(0)
	v_add_f32_e32 v0, v0, v14
	v_fmamk_f32 v0, v0, 0x3c800000, v185
	v_mul_f32_e32 v14, 0x4b800000, v0
	v_cmp_gt_f32_e32 vcc, s80, v0
	s_nop 1
	v_cndmask_b32_e32 v0, v0, v14, vcc
	v_rsq_f32_e32 v0, v0
	v_lshlrev_b32_e32 v14, 1, v15
	v_add3_u32 v15, 0, v16, v14
	v_add3_u32 v14, 0, v14, v16
	v_mul_f32_e32 v16, 0x45800000, v0
	v_cndmask_b32_e32 v0, v0, v16, vcc
	v_pk_mul_f32 v[6:7], v[6:7], v[0:1] op_sel_hi:[1,0]
	v_pk_mul_f32 v[2:3], v[2:3], v[0:1] op_sel_hi:[1,0]
	v_cvt_pk_bf16_f32 v6, v6, v7
	ds_write_b16 v15, v6
	ds_write_b16_d16_hi v14, v6 offset:272
	v_pk_mul_f32 v[6:7], v[24:25], v[0:1] op_sel_hi:[1,0]
	v_pk_mov_b32 v[2:3], v[2:3], v[2:3] op_sel:[1,0]
	v_cvt_pk_bf16_f32 v6, v6, v7
	ds_write_b16 v15, v6 offset:544
	ds_write_b16_d16_hi v14, v6 offset:816
	v_pk_mul_f32 v[6:7], v[8:9], v[0:1] op_sel_hi:[1,0]
	v_cvt_pk_bf16_f32 v2, v2, v3
	v_cvt_pk_bf16_f32 v6, v6, v7
	ds_write_b16 v15, v6 offset:1088
	ds_write_b16_d16_hi v14, v6 offset:1360
	v_pk_mul_f32 v[6:7], v[30:31], v[0:1] op_sel_hi:[1,0]
	v_ashrrev_i32_e32 v24, 7, v44
	v_cvt_pk_bf16_f32 v6, v6, v7
	ds_write_b16 v15, v6 offset:1632
	ds_write_b16_d16_hi v14, v6 offset:1904
	v_pk_mul_f32 v[6:7], v[10:11], v[0:1] op_sel_hi:[1,0]
	v_mov_b32_e32 v8, v1
	v_pk_mov_b32 v[6:7], v[6:7], v[6:7] op_sel:[1,0]
	v_mov_b32_e32 v9, v1
	v_cvt_pk_bf16_f32 v6, v6, v7
	ds_write_b16 v15, v6 offset:2176
	ds_write_b16_d16_hi v14, v6 offset:2448
	ds_write_b16 v15, v2 offset:2720
	ds_write_b16_d16_hi v14, v2 offset:2992
	v_pk_mul_f32 v[2:3], v[12:13], v[0:1] op_sel_hi:[1,0]
	v_mov_b32_e32 v6, v1
	v_pk_mov_b32 v[2:3], v[2:3], v[2:3] op_sel:[1,0]
	v_mov_b32_e32 v7, v1
	v_cvt_pk_bf16_f32 v2, v2, v3
	ds_write_b16 v15, v2 offset:3264
	ds_write_b16_d16_hi v14, v2 offset:3536
	v_pk_mul_f32 v[2:3], v[4:5], v[0:1] op_sel_hi:[1,0]
	v_lshrrev_b32_e32 v4, 1, v44
	v_pk_mov_b32 v[2:3], v[2:3], v[2:3] op_sel:[1,0]
	v_mov_b32_e32 v5, v1
	v_cvt_pk_bf16_f32 v0, v2, v3
	ds_write_b16 v15, v0 offset:3808
	ds_write_b16_d16_hi v14, v0 offset:4080
	v_and_b32_e32 v0, 31, v44
	v_lshlrev_b32_e32 v2, 5, v24
	v_ashrrev_i32_e32 v19, 31, v2
	v_or_b32_e32 v18, v2, v0
	v_lshl_add_u64 v[2:3], s[2:3], 0, v[18:19]
	v_and_b32_e32 v19, 32, v4
	v_lshlrev_b64 v[2:3], 8, v[2:3]
	v_or_b32_e32 v0, v19, v0
	v_mul_u32_u24_e32 v4, 0x110, v0
	v_lshl_add_u64 v[2:3], s[30:31], 0, v[2:3]
	v_lshlrev_b32_e32 v0, 4, v22
	v_lshl_add_u64 v[20:21], v[2:3], 0, v[0:1]
	v_add3_u32 v23, 0, v4, v0
	v_mov_b32_e32 v2, v1
	v_mov_b32_e32 v3, v1
	v_mov_b32_e32 v4, v1
	v_mov_b32_e32 v10, v1
	v_mov_b32_e32 v11, v1
	v_mov_b32_e32 v12, v1
	v_mov_b32_e32 v13, v1
	v_mov_b32_e32 v14, v1
	v_mov_b32_e32 v15, v1
	v_mov_b32_e32 v0, v1
	v_mov_b64_e32 v[16:17], v[14:15]
	v_cmp_lt_i32_e32 vcc, -1, v24
	v_mov_b64_e32 v[14:15], v[12:13]
	v_mov_b64_e32 v[12:13], v[10:11]
	v_mov_b64_e32 v[10:11], v[8:9]
	v_mov_b64_e32 v[8:9], v[6:7]
	v_mov_b64_e32 v[6:7], v[4:5]
	v_mov_b64_e32 v[4:5], v[2:3]
	v_mov_b64_e32 v[2:3], v[0:1]
	global_load_dwordx4 v[50:53], v[20:21], off
	global_load_dwordx4 v[54:57], v[20:21], off offset:32
	global_load_dwordx4 v[58:61], v[20:21], off offset:64
	global_load_dwordx4 v[62:65], v[20:21], off offset:96
	global_load_dwordx4 v[66:69], v[20:21], off offset:128
	global_load_dwordx4 v[70:73], v[20:21], off offset:160
	global_load_dwordx4 v[74:77], v[20:21], off offset:192
	global_load_dwordx4 v[78:81], v[20:21], off offset:224
	s_waitcnt lgkmcnt(0)
	s_barrier
	ds_read_b128 v[82:85], v23
	ds_read_b128 v[86:89], v23 offset:32
	ds_read_b128 v[90:93], v23 offset:64
	ds_read_b128 v[94:97], v23 offset:96
	ds_read_b128 v[98:101], v23 offset:128
	ds_read_b128 v[102:105], v23 offset:160
	ds_read_b128 v[106:109], v23 offset:192
	ds_read_b128 v[110:113], v23 offset:224
	s_mov_b64 s[4:5], exec
	v_cmp_lt_i32_e32 vcc, -1, v24
	s_cbranch_vccz .LBB0_1491
	s_waitcnt vmcnt(6) lgkmcnt(6)
	v_mfma_f32_32x32x16_bf16 v[2:17], v[82:85], v[50:53], 0
	v_mfma_f32_32x32x16_bf16 v[2:17], v[86:89], v[54:57], v[2:17]
	v_cmp_lt_i32_e32 vcc, 0, v24
	s_cbranch_vccz .LBB0_1491
	s_waitcnt vmcnt(4) lgkmcnt(4)
	v_mfma_f32_32x32x16_bf16 v[2:17], v[90:93], v[58:61], v[2:17]
	v_mfma_f32_32x32x16_bf16 v[2:17], v[94:97], v[62:65], v[2:17]
	v_cmp_lt_i32_e32 vcc, 1, v24
	s_cbranch_vccz .LBB0_1491
	s_waitcnt vmcnt(2) lgkmcnt(2)
	v_mfma_f32_32x32x16_bf16 v[2:17], v[98:101], v[66:69], v[2:17]
	v_mfma_f32_32x32x16_bf16 v[2:17], v[102:105], v[70:73], v[2:17]
	v_cmp_lt_i32_e32 vcc, 2, v24
	s_cbranch_vccz .LBB0_1491
	s_waitcnt vmcnt(0) lgkmcnt(0)
	v_mfma_f32_32x32x16_bf16 v[2:17], v[106:109], v[74:77], v[2:17]
	v_mfma_f32_32x32x16_bf16 v[2:17], v[110:113], v[78:81], v[2:17]
	s_branch .LBB0_1491

.LBB0_1512:
	v_ashrrev_i32_e32 v0, 2, v50
	v_add_u32_e32 v0, v0, v51
	v_cmp_gt_i32_e32 vcc, s85, v0
	s_and_b64 s[22:23], s[2:3], vcc
	v_mov_b32_e32 v60, 0
	v_mov_b32_e32 v61, 0
	v_mov_b32_e32 v62, 0
	v_mov_b32_e32 v63, 0
	v_mov_b32_e32 v64, 0
	v_mov_b32_e32 v65, 0
	v_mov_b32_e32 v66, 0
	v_mov_b32_e32 v67, 0
	v_mov_b32_e32 v68, 0
	v_mov_b32_e32 v69, 0
	v_mov_b32_e32 v70, 0
	v_mov_b32_e32 v71, 0
	v_mov_b32_e32 v72, 0
	v_mov_b32_e32 v73, 0
	v_mov_b32_e32 v74, 0
	v_mov_b32_e32 v75, 0
	s_and_saveexec_b64 s[14:15], s[22:23]
	s_cbranch_execz .Lcmp_noa
	v_add_u32_e32 v0, s21, v0
	v_mad_i64_i32 v[34:35], s[22:23], v0, s84, v[42:43]
	global_load_dwordx4 v[60:63], v[34:35], off
	global_load_dwordx4 v[64:67], v[34:35], off offset:32
	global_load_dwordx4 v[68:71], v[34:35], off offset:64
	global_load_dwordx4 v[72:75], v[34:35], off offset:96
.Lcmp_noa:
	s_or_b64 exec, exec, s[14:15]
	v_lshl_add_u64 v[46:47], v[44:45], 0, s[6:7]
	v_add_co_u32_e32 v38, vcc, 0x13800000, v46
	s_nop 1
	v_addc_co_u32_e32 v39, vcc, 0, v47, vcc
	v_add_co_u32_e32 v56, vcc, 0x13820000, v46
	s_nop 1
	v_addc_co_u32_e32 v57, vcc, 0, v47, vcc
	global_load_dwordx4 v[76:79], v[38:39], off
	global_load_dwordx4 v[80:83], v[56:57], off
	global_load_dwordx4 v[84:87], v[38:39], off offset:32
	global_load_dwordx4 v[88:91], v[56:57], off offset:32
	global_load_dwordx4 v[92:95], v[38:39], off offset:64
	global_load_dwordx4 v[96:99], v[56:57], off offset:64
	global_load_dwordx4 v[100:103], v[38:39], off offset:96
	global_load_dwordx4 v[104:107], v[56:57], off offset:96
	s_add_u32 s6, s6, 0x80
	s_addc_u32 s7, s7, 0
	v_add_u32_e32 v50, 4, v50
	s_waitcnt vmcnt(7)
	v_mfma_f32_32x32x16_bf16 v[2:17], v[60:63], v[76:79], v[2:17]
	s_waitcnt vmcnt(6)
	v_mfma_f32_32x32x16_bf16 v[18:33], v[60:63], v[80:83], v[18:33]
	s_waitcnt vmcnt(5)
	v_mfma_f32_32x32x16_bf16 v[2:17], v[64:67], v[84:87], v[2:17]
	s_waitcnt vmcnt(4)
	v_mfma_f32_32x32x16_bf16 v[18:33], v[64:67], v[88:91], v[18:33]
	s_waitcnt vmcnt(3)
	v_mfma_f32_32x32x16_bf16 v[2:17], v[68:71], v[92:95], v[2:17]
	s_waitcnt vmcnt(2)
	v_mfma_f32_32x32x16_bf16 v[18:33], v[68:71], v[96:99], v[18:33]
	s_waitcnt vmcnt(1)
	v_mfma_f32_32x32x16_bf16 v[2:17], v[72:75], v[100:103], v[2:17]
	s_waitcnt vmcnt(0)
	v_mfma_f32_32x32x16_bf16 v[18:33], v[72:75], v[104:107], v[18:33]
	s_cmpk_eq_i32 s6, 0x200
	s_cbranch_scc0 .LBB0_1512

.LBB0_1521:
	global_load_dword v58, v[4:5], off offset:-1792
	global_load_dword v60, v[4:5], off offset:-1536
	global_load_dword v62, v[4:5], off offset:-1280
	global_load_dword v64, v[4:5], off offset:-1024
	global_load_dword v66, v[4:5], off offset:-768
	global_load_dword v68, v[4:5], off offset:-512
	global_load_dword v70, v[4:5], off offset:-256
	global_load_dword v72, v[4:5], off
	v_add_u32_e32 v17, s2, v16
	v_add_u32_e32 v18, 0x10100, v17
	v_add_u32_e32 v22, 0x10200, v17
	ds_read_b128 v[18:21], v18
	ds_read_b128 v[22:25], v22
	s_add_i32 s2, s2, 32
	s_cmp_eq_u32 s2, 0
	s_waitcnt lgkmcnt(1)
	v_mov_b32_e32 v26, v18
	s_waitcnt lgkmcnt(0)
	v_mov_b32_e32 v27, v22
	v_add_u32_e32 v18, 0x10300, v17
	v_mov_b32_e32 v22, v19
	v_mov_b32_e32 v19, v24
	v_mov_b32_e32 v24, v21
	s_waitcnt vmcnt(7)
	v_pk_fma_f32 v[6:7], v[58:59], v[26:27], v[6:7] op_sel_hi:[0,1,1]
	ds_read_b128 v[26:29], v18
	v_add_u32_e32 v18, 0x10400, v17
	ds_read_b128 v[30:33], v18
	v_mov_b32_e32 v18, v20
	s_waitcnt lgkmcnt(1)
	v_mov_b32_e32 v34, v26
	s_waitcnt lgkmcnt(0)
	v_mov_b32_e32 v35, v30
	v_pk_fma_f32 v[8:9], v[58:59], v[34:35], v[8:9] op_sel_hi:[0,1,1]
	v_mov_b32_e32 v30, v27
	s_waitcnt vmcnt(6)
	v_pk_fma_f32 v[6:7], v[60:61], v[22:23], v[6:7] op_sel_hi:[0,1,1]
	v_pk_fma_f32 v[8:9], v[60:61], v[30:31], v[8:9] op_sel_hi:[0,1,1]
	s_waitcnt vmcnt(5)
	v_pk_fma_f32 v[6:7], v[62:63], v[18:19], v[6:7] op_sel_hi:[0,1,1]
	v_mov_b32_e32 v18, v28
	v_mov_b32_e32 v19, v32
	v_pk_fma_f32 v[8:9], v[62:63], v[18:19], v[8:9] op_sel_hi:[0,1,1]
	v_mov_b32_e32 v32, v29
	v_add_u32_e32 v18, 0x10210, v17
	ds_read_b128 v[18:21], v18
	s_waitcnt vmcnt(4)
	v_pk_fma_f32 v[22:23], v[64:65], v[24:25], v[6:7] op_sel_hi:[0,1,1]
	v_pk_fma_f32 v[30:31], v[64:65], v[32:33], v[8:9] op_sel_hi:[0,1,1]
	v_add_u32_e32 v6, 0x10110, v17
	ds_read_b128 v[6:9], v6
	s_waitcnt lgkmcnt(1)
	v_mov_b32_e32 v25, v18
	s_waitcnt lgkmcnt(0)
	v_mov_b32_e32 v24, v6
	v_add_u32_e32 v6, 0x10310, v17
	v_mov_b32_e32 v18, v7
	s_waitcnt vmcnt(3)
	v_pk_fma_f32 v[32:33], v[66:67], v[24:25], v[22:23] op_sel_hi:[0,1,1]
	ds_read_b128 v[22:25], v6
	v_add_u32_e32 v6, 0x10410, v17
	ds_read_b128 v[26:29], v6
	s_waitcnt lgkmcnt(1)
	v_mov_b32_e32 v34, v22
	v_mov_b32_e32 v22, v8
	s_waitcnt lgkmcnt(0)
	v_mov_b32_e32 v35, v26
	v_pk_fma_f32 v[30:31], v[66:67], v[34:35], v[30:31] op_sel_hi:[0,1,1]
	v_mov_b32_e32 v26, v23
	v_mov_b32_e32 v23, v20
	v_mov_b32_e32 v20, v9
	s_waitcnt vmcnt(2)
	v_pk_fma_f32 v[6:7], v[68:69], v[18:19], v[32:33] op_sel_hi:[0,1,1]
	v_pk_fma_f32 v[18:19], v[68:69], v[26:27], v[30:31] op_sel_hi:[0,1,1]
	s_waitcnt vmcnt(1)
	v_pk_fma_f32 v[6:7], v[70:71], v[22:23], v[6:7] op_sel_hi:[0,1,1]
	v_mov_b32_e32 v22, v24
	v_mov_b32_e32 v23, v28
	v_pk_fma_f32 v[18:19], v[70:71], v[22:23], v[18:19] op_sel_hi:[0,1,1]
	v_mov_b32_e32 v28, v25
	v_lshl_add_u64 v[4:5], v[4:5], 0, s[90:91]
	s_waitcnt vmcnt(0)
	v_pk_fma_f32 v[6:7], v[72:73], v[20:21], v[6:7] op_sel_hi:[0,1,1]
	v_pk_fma_f32 v[8:9], v[72:73], v[28:29], v[18:19] op_sel_hi:[0,1,1]
	s_cbranch_scc0 .LBB0_1521
	s_lshl_b32 s4, s18, 14
	s_lshl_b32 s2, s19, 15
	s_or_b32 s2, s2, s4
	s_add_u32 s2, s78, s2
	s_addc_u32 s3, s79, 0
	s_lshl_b32 s5, s17, 15
	s_or_b32 s4, s4, s5
	s_add_u32 s6, s89, s4
	s_addc_u32 s7, s46, 0
	s_add_i32 s14, 0, 0x12000
	v_lshl_add_u32 v16, v40, 2, s14
	v_add_u32_e32 v4, v16, v3
	ds_write2st64_b32 v4, v6, v7 offset1:1
	ds_write2st64_b32 v4, v8, v9 offset0:2 offset1:3
	v_lshlrev_b32_e32 v0, 8, v40
	v_add_u32_e32 v8, s54, v2
	v_lshl_add_u64 v[6:7], s[2:3], 0, v[0:1]
	v_cmp_gt_u32_e64 s[2:3], 32, v40
	v_cmp_gt_i32_e64 s[4:5], s68, v8
	s_mov_b64 s[12:13], -1
	s_and_b64 vcc, exec, s[0:1]
	s_waitcnt lgkmcnt(0)
	s_barrier
	s_cbranch_vccz .LBB0_1526
	v_mov_b32_e32 v0, 0
	s_and_saveexec_b64 s[12:13], s[4:5]
	s_cbranch_execz .LBB0_1525
	ds_read_b32 v0, v4
	s_waitcnt lgkmcnt(0)
	v_cvt_pk_bf16_f32 v0, v0, s0
